# GLU epilogue by hand: all 32 gate loads in flight at once (the compiler's waited for them one or two at a time), lane exchange and 16-byte stores for the second half of cat
# speedup vs baseline: 1.0256x; 1.0023x over previous
.LBB0_1177:
	ds_read_b128 v[140:143], v163
	ds_read_b128 v[144:147], v163 offset:1024
	ds_read_b128 v[148:151], v163 offset:2048
	ds_read_b128 v[152:155], v163 offset:3072
	s_add_u32 s10, s8, 0xfffe0080
	s_addc_u32 s11, s9, -1
	s_cmp_eq_u32 s61, 4
	s_cselect_b32 s29, s23, s11
	s_cselect_b32 s28, s57, s10
	s_cselect_b32 s11, s21, s60
	s_cselect_b32 s10, s58, s59
	v_lshl_add_u64 v[202:203], s[8:9], 0, v[134:135]
	s_add_i32 m0, s36, 0xc000
	ds_read_b128 v[156:159], v164
	ds_read_b128 v[166:169], v164 offset:1024
	ds_read_b128 v[178:181], v164 offset:2048
	ds_read_b128 v[182:185], v164 offset:3072
	ds_read_b128 v[186:189], v164 offset:4096
	ds_read_b128 v[190:193], v164 offset:5120
	ds_read_b128 v[194:197], v164 offset:6144
	ds_read_b128 v[198:201], v164 offset:7168
	global_load_lds_dwordx4 v[202:203], off
	v_lshl_add_u64 v[202:203], s[8:9], 0, v[132:133]
	s_add_i32 m0, s36, 0xe000
	s_nop 0
	global_load_lds_dwordx4 v[202:203], off
	s_waitcnt lgkmcnt(8)
	s_barrier
	s_waitcnt lgkmcnt(0)
	s_setprio 1
	s_waitcnt lgkmcnt(0)
	v_mfma_f32_16x16x32_bf16 v[124:127], v[140:143], v[156:159], v[124:127]
	v_mfma_f32_16x16x32_bf16 v[120:123], v[148:151], v[156:159], v[120:123]
	v_mfma_f32_16x16x32_bf16 v[116:119], v[140:143], v[178:181], v[116:119]
	v_mfma_f32_16x16x32_bf16 v[112:115], v[148:151], v[178:181], v[112:115]
	v_mfma_f32_16x16x32_bf16 v[108:111], v[140:143], v[186:189], v[108:111]
	v_mfma_f32_16x16x32_bf16 v[104:107], v[148:151], v[186:189], v[104:107]
	v_mfma_f32_16x16x32_bf16 v[100:103], v[140:143], v[194:197], v[100:103]
	v_mfma_f32_16x16x32_bf16 v[96:99], v[148:151], v[194:197], v[96:99]
	v_mfma_f32_16x16x32_bf16 v[124:127], v[144:147], v[166:169], v[124:127]
	v_mfma_f32_16x16x32_bf16 v[120:123], v[152:155], v[166:169], v[120:123]
	v_mfma_f32_16x16x32_bf16 v[116:119], v[144:147], v[182:185], v[116:119]
	v_mfma_f32_16x16x32_bf16 v[112:115], v[152:155], v[182:185], v[112:115]
	v_mfma_f32_16x16x32_bf16 v[108:111], v[144:147], v[190:193], v[108:111]
	v_mfma_f32_16x16x32_bf16 v[104:107], v[152:155], v[190:193], v[104:107]
	v_mfma_f32_16x16x32_bf16 v[100:103], v[144:147], v[198:201], v[100:103]
	v_mfma_f32_16x16x32_bf16 v[96:99], v[152:155], v[198:201], v[96:99]
	s_setprio 0
	s_barrier
	s_add_i32 s33, s55, s35
	v_lshl_add_u64 v[218:219], s[10:11], 0, v[130:131]
	s_mov_b32 m0, s33
	ds_read_b128 v[202:205], v165
	ds_read_b128 v[206:209], v165 offset:1024
	ds_read_b128 v[210:213], v165 offset:2048
	ds_read_b128 v[214:217], v165 offset:3072
	global_load_lds_dwordx4 v[218:219], off
	v_lshl_add_u64 v[220:221], s[10:11], 0, v[128:129]
	s_add_i32 m0, s33, 0x2000
	s_nop 0
	global_load_lds_dwordx4 v[220:221], off
	s_barrier
	s_waitcnt lgkmcnt(0)
	s_setprio 1
	s_waitcnt lgkmcnt(0)
	v_mfma_f32_16x16x32_bf16 v[92:95], v[202:205], v[156:159], v[92:95]
	v_mfma_f32_16x16x32_bf16 v[88:91], v[210:213], v[156:159], v[88:91]
	v_mfma_f32_16x16x32_bf16 v[84:87], v[202:205], v[178:181], v[84:87]
	v_mfma_f32_16x16x32_bf16 v[80:83], v[210:213], v[178:181], v[80:83]
	v_mfma_f32_16x16x32_bf16 v[76:79], v[202:205], v[186:189], v[76:79]
	v_mfma_f32_16x16x32_bf16 v[72:75], v[210:213], v[186:189], v[72:75]
	v_mfma_f32_16x16x32_bf16 v[68:71], v[202:205], v[194:197], v[68:71]
	v_mfma_f32_16x16x32_bf16 v[64:67], v[210:213], v[194:197], v[64:67]
	v_mfma_f32_16x16x32_bf16 v[92:95], v[206:209], v[166:169], v[92:95]
	v_mfma_f32_16x16x32_bf16 v[88:91], v[214:217], v[166:169], v[88:91]
	v_mfma_f32_16x16x32_bf16 v[84:87], v[206:209], v[182:185], v[84:87]
	v_mfma_f32_16x16x32_bf16 v[80:83], v[214:217], v[182:185], v[80:83]
	v_mfma_f32_16x16x32_bf16 v[76:79], v[206:209], v[190:193], v[76:79]
	v_mfma_f32_16x16x32_bf16 v[72:75], v[214:217], v[190:193], v[72:75]
	v_mfma_f32_16x16x32_bf16 v[68:71], v[206:209], v[198:201], v[68:71]
	v_mfma_f32_16x16x32_bf16 v[64:67], v[214:217], v[198:201], v[64:67]
	s_setprio 0
	s_mov_b32 m0, s36
	v_lshl_add_u64 v[222:223], s[28:29], 0, v[130:131]
	s_barrier
	ds_read_b128 v[156:159], v164 offset:16384
	ds_read_b128 v[166:169], v164 offset:17408
	ds_read_b128 v[178:181], v164 offset:18432
	ds_read_b128 v[182:185], v164 offset:19456
	ds_read_b128 v[186:189], v164 offset:20480
	ds_read_b128 v[190:193], v164 offset:21504
	ds_read_b128 v[194:197], v164 offset:22528
	ds_read_b128 v[198:201], v164 offset:23552
	global_load_lds_dwordx4 v[222:223], off
	v_lshl_add_u64 v[224:225], s[28:29], 0, v[128:129]
	s_mov_b32 m0, s37
	s_nop 0
	global_load_lds_dwordx4 v[224:225], off
	s_barrier
	s_waitcnt lgkmcnt(0)
	s_setprio 1
	s_waitcnt lgkmcnt(0)
	v_mfma_f32_16x16x32_bf16 v[60:63], v[140:143], v[156:159], v[60:63]
	v_mfma_f32_16x16x32_bf16 v[56:59], v[148:151], v[156:159], v[56:59]
	v_mfma_f32_16x16x32_bf16 v[52:55], v[140:143], v[178:181], v[52:55]
	v_mfma_f32_16x16x32_bf16 v[48:51], v[148:151], v[178:181], v[48:51]
	v_mfma_f32_16x16x32_bf16 v[44:47], v[140:143], v[186:189], v[44:47]
	v_mfma_f32_16x16x32_bf16 v[40:43], v[148:151], v[186:189], v[40:43]
	v_mfma_f32_16x16x32_bf16 v[36:39], v[140:143], v[194:197], v[36:39]
	v_mfma_f32_16x16x32_bf16 v[32:35], v[148:151], v[194:197], v[32:35]
	v_mfma_f32_16x16x32_bf16 v[60:63], v[144:147], v[166:169], v[60:63]
	v_mfma_f32_16x16x32_bf16 v[56:59], v[152:155], v[166:169], v[56:59]
	v_mfma_f32_16x16x32_bf16 v[52:55], v[144:147], v[182:185], v[52:55]
	v_mfma_f32_16x16x32_bf16 v[48:51], v[152:155], v[182:185], v[48:51]
	v_mfma_f32_16x16x32_bf16 v[44:47], v[144:147], v[190:193], v[44:47]
	v_mfma_f32_16x16x32_bf16 v[40:43], v[152:155], v[190:193], v[40:43]
	v_mfma_f32_16x16x32_bf16 v[36:39], v[144:147], v[198:201], v[36:39]
	v_mfma_f32_16x16x32_bf16 v[32:35], v[152:155], v[198:201], v[32:35]
	s_setprio 0
	s_barrier
	s_add_u32 s62, s10, 0x20000
	s_addc_u32 s63, s11, 0
	s_add_i32 s33, s56, s35
	v_lshl_add_u64 v[140:141], s[62:63], 0, v[130:131]
	s_mov_b32 m0, s33
	s_nop 0
	global_load_lds_dwordx4 v[140:141], off
	v_lshl_add_u64 v[140:141], s[62:63], 0, v[128:129]
	s_add_i32 m0, s33, 0x2000
	s_nop 0
	global_load_lds_dwordx4 v[140:141], off
	s_waitcnt vmcnt(6)
	s_barrier
	s_setprio 1
	v_mfma_f32_16x16x32_bf16 v[28:31], v[202:205], v[156:159], v[28:31]
	v_mfma_f32_16x16x32_bf16 v[24:27], v[210:213], v[156:159], v[24:27]
	v_mfma_f32_16x16x32_bf16 v[20:23], v[202:205], v[178:181], v[20:23]
	v_mfma_f32_16x16x32_bf16 v[16:19], v[210:213], v[178:181], v[16:19]
	v_mfma_f32_16x16x32_bf16 v[12:15], v[202:205], v[186:189], v[12:15]
	v_mfma_f32_16x16x32_bf16 v[8:11], v[210:213], v[186:189], v[8:11]
	v_mfma_f32_16x16x32_bf16 v[4:7], v[202:205], v[194:197], v[4:7]
	v_mfma_f32_16x16x32_bf16 v[0:3], v[210:213], v[194:197], v[0:3]
	v_mfma_f32_16x16x32_bf16 v[28:31], v[206:209], v[166:169], v[28:31]
	v_mfma_f32_16x16x32_bf16 v[24:27], v[214:217], v[166:169], v[24:27]
	v_mfma_f32_16x16x32_bf16 v[20:23], v[206:209], v[182:185], v[20:23]
	v_mfma_f32_16x16x32_bf16 v[16:19], v[214:217], v[182:185], v[16:19]
	v_mfma_f32_16x16x32_bf16 v[12:15], v[206:209], v[190:193], v[12:15]
	v_mfma_f32_16x16x32_bf16 v[8:11], v[214:217], v[190:193], v[8:11]
	v_mfma_f32_16x16x32_bf16 v[4:7], v[206:209], v[198:201], v[4:7]
	v_mfma_f32_16x16x32_bf16 v[0:3], v[214:217], v[198:201], v[0:3]
	s_setprio 0
	s_add_i32 s33, 0, 0x18000
	v_add_u32_e32 v152, s33, v161
	s_barrier
	ds_read_b128 v[140:143], v152
	ds_read_b128 v[144:147], v152 offset:1024
	ds_read_b128 v[148:151], v152 offset:2048
	ds_read_b128 v[152:155], v152 offset:3072
	s_add_u32 s28, s28, 0x20000
	s_addc_u32 s29, s29, 0
	s_mov_b32 m0, s40
	v_lshl_add_u64 v[202:203], s[28:29], 0, v[130:131]
	ds_read_b128 v[156:159], v164 offset:32768
	ds_read_b128 v[166:169], v164 offset:33792
	ds_read_b128 v[178:181], v164 offset:34816
	ds_read_b128 v[182:185], v164 offset:35840
	ds_read_b128 v[186:189], v164 offset:36864
	ds_read_b128 v[190:193], v164 offset:37888
	ds_read_b128 v[194:197], v164 offset:38912
	ds_read_b128 v[198:201], v164 offset:39936
	global_load_lds_dwordx4 v[202:203], off
	v_lshl_add_u64 v[202:203], s[28:29], 0, v[128:129]
	s_mov_b32 m0, s41
	s_nop 0
	global_load_lds_dwordx4 v[202:203], off
	s_waitcnt lgkmcnt(8)
	s_barrier
	s_waitcnt lgkmcnt(0)
	s_setprio 1
	s_waitcnt lgkmcnt(0)
	v_mfma_f32_16x16x32_bf16 v[124:127], v[140:143], v[156:159], v[124:127]
	v_mfma_f32_16x16x32_bf16 v[120:123], v[148:151], v[156:159], v[120:123]
	v_mfma_f32_16x16x32_bf16 v[116:119], v[140:143], v[178:181], v[116:119]
	v_mfma_f32_16x16x32_bf16 v[112:115], v[148:151], v[178:181], v[112:115]
	v_mfma_f32_16x16x32_bf16 v[108:111], v[140:143], v[186:189], v[108:111]
	v_mfma_f32_16x16x32_bf16 v[104:107], v[148:151], v[186:189], v[104:107]
	v_mfma_f32_16x16x32_bf16 v[100:103], v[140:143], v[194:197], v[100:103]
	v_mfma_f32_16x16x32_bf16 v[96:99], v[148:151], v[194:197], v[96:99]
	v_mfma_f32_16x16x32_bf16 v[124:127], v[144:147], v[166:169], v[124:127]
	v_mfma_f32_16x16x32_bf16 v[120:123], v[152:155], v[166:169], v[120:123]
	v_mfma_f32_16x16x32_bf16 v[116:119], v[144:147], v[182:185], v[116:119]
	v_mfma_f32_16x16x32_bf16 v[112:115], v[152:155], v[182:185], v[112:115]
	v_mfma_f32_16x16x32_bf16 v[108:111], v[144:147], v[190:193], v[108:111]
	v_mfma_f32_16x16x32_bf16 v[104:107], v[152:155], v[190:193], v[104:107]
	v_mfma_f32_16x16x32_bf16 v[100:103], v[144:147], v[198:201], v[100:103]
	v_mfma_f32_16x16x32_bf16 v[96:99], v[152:155], v[198:201], v[96:99]
	s_setprio 0
	s_barrier
	s_add_i32 s28, 0, 0x1c000
	s_add_i32 s29, s33, s35
	v_add_u32_e32 v177, s28, v161
	v_lshl_add_u64 v[218:219], v[218:219], 0, s[16:17]
	s_mov_b32 m0, s29
	ds_read_b128 v[202:205], v177
	ds_read_b128 v[206:209], v177 offset:1024
	ds_read_b128 v[210:213], v177 offset:2048
	ds_read_b128 v[214:217], v177 offset:3072
	global_load_lds_dwordx4 v[218:219], off
	v_lshl_add_u64 v[218:219], v[220:221], 0, s[16:17]
	s_add_i32 m0, s29, 0x2000
	s_nop 0
	global_load_lds_dwordx4 v[218:219], off
	s_barrier
	s_waitcnt lgkmcnt(0)
	s_setprio 1
	s_waitcnt lgkmcnt(0)
	v_mfma_f32_16x16x32_bf16 v[92:95], v[202:205], v[156:159], v[92:95]
	v_mfma_f32_16x16x32_bf16 v[88:91], v[210:213], v[156:159], v[88:91]
	v_mfma_f32_16x16x32_bf16 v[84:87], v[202:205], v[178:181], v[84:87]
	v_mfma_f32_16x16x32_bf16 v[80:83], v[210:213], v[178:181], v[80:83]
	v_mfma_f32_16x16x32_bf16 v[76:79], v[202:205], v[186:189], v[76:79]
	v_mfma_f32_16x16x32_bf16 v[72:75], v[210:213], v[186:189], v[72:75]
	v_mfma_f32_16x16x32_bf16 v[68:71], v[202:205], v[194:197], v[68:71]
	v_mfma_f32_16x16x32_bf16 v[64:67], v[210:213], v[194:197], v[64:67]
	v_mfma_f32_16x16x32_bf16 v[92:95], v[206:209], v[166:169], v[92:95]
	v_mfma_f32_16x16x32_bf16 v[88:91], v[214:217], v[166:169], v[88:91]
	v_mfma_f32_16x16x32_bf16 v[84:87], v[206:209], v[182:185], v[84:87]
	v_mfma_f32_16x16x32_bf16 v[80:83], v[214:217], v[182:185], v[80:83]
	v_mfma_f32_16x16x32_bf16 v[76:79], v[206:209], v[190:193], v[76:79]
	v_mfma_f32_16x16x32_bf16 v[72:75], v[214:217], v[190:193], v[72:75]
	v_mfma_f32_16x16x32_bf16 v[68:71], v[206:209], v[198:201], v[68:71]
	v_mfma_f32_16x16x32_bf16 v[64:67], v[214:217], v[198:201], v[64:67]
	s_setprio 0
	s_mov_b32 m0, s47
	v_lshl_add_u64 v[218:219], v[222:223], 0, s[16:17]
	s_barrier
	ds_read_b128 v[156:159], v164 offset:49152
	ds_read_b128 v[166:169], v164 offset:50176
	ds_read_b128 v[178:181], v164 offset:51200
	ds_read_b128 v[182:185], v164 offset:52224
	ds_read_b128 v[186:189], v164 offset:53248
	ds_read_b128 v[190:193], v164 offset:54272
	ds_read_b128 v[194:197], v164 offset:55296
	ds_read_b128 v[198:201], v164 offset:56320
	global_load_lds_dwordx4 v[218:219], off
	v_lshl_add_u64 v[218:219], v[224:225], 0, s[16:17]
	s_mov_b32 m0, s52
	s_nop 0
	global_load_lds_dwordx4 v[218:219], off
	s_barrier
	s_waitcnt lgkmcnt(0)
	s_setprio 1
	s_waitcnt lgkmcnt(0)
	v_mfma_f32_16x16x32_bf16 v[60:63], v[140:143], v[156:159], v[60:63]
	v_mfma_f32_16x16x32_bf16 v[56:59], v[148:151], v[156:159], v[56:59]
	v_mfma_f32_16x16x32_bf16 v[52:55], v[140:143], v[178:181], v[52:55]
	v_mfma_f32_16x16x32_bf16 v[48:51], v[148:151], v[178:181], v[48:51]
	v_mfma_f32_16x16x32_bf16 v[44:47], v[140:143], v[186:189], v[44:47]
	v_mfma_f32_16x16x32_bf16 v[40:43], v[148:151], v[186:189], v[40:43]
	v_mfma_f32_16x16x32_bf16 v[36:39], v[140:143], v[194:197], v[36:39]
	v_mfma_f32_16x16x32_bf16 v[32:35], v[148:151], v[194:197], v[32:35]
	v_mfma_f32_16x16x32_bf16 v[60:63], v[144:147], v[166:169], v[60:63]
	v_mfma_f32_16x16x32_bf16 v[56:59], v[152:155], v[166:169], v[56:59]
	v_mfma_f32_16x16x32_bf16 v[52:55], v[144:147], v[182:185], v[52:55]
	v_mfma_f32_16x16x32_bf16 v[48:51], v[152:155], v[182:185], v[48:51]
	v_mfma_f32_16x16x32_bf16 v[44:47], v[144:147], v[190:193], v[44:47]
	v_mfma_f32_16x16x32_bf16 v[40:43], v[152:155], v[190:193], v[40:43]
	v_mfma_f32_16x16x32_bf16 v[36:39], v[144:147], v[198:201], v[36:39]
	v_mfma_f32_16x16x32_bf16 v[32:35], v[152:155], v[198:201], v[32:35]
	s_setprio 0
	s_barrier
	s_add_u32 s10, s10, 0x20080
	s_addc_u32 s11, s11, 0
	s_add_i32 s28, s28, s35
	v_lshl_add_u64 v[140:141], s[10:11], 0, v[130:131]
	s_mov_b32 m0, s28
	s_nop 0
	global_load_lds_dwordx4 v[140:141], off
	v_lshl_add_u64 v[140:141], s[10:11], 0, v[128:129]
	s_add_i32 m0, s28, 0x2000
	s_nop 0
	global_load_lds_dwordx4 v[140:141], off
	s_waitcnt vmcnt(6)
	s_barrier
	s_setprio 1
	v_mfma_f32_16x16x32_bf16 v[28:31], v[202:205], v[156:159], v[28:31]
	v_mfma_f32_16x16x32_bf16 v[24:27], v[210:213], v[156:159], v[24:27]
	v_mfma_f32_16x16x32_bf16 v[20:23], v[202:205], v[178:181], v[20:23]
	v_mfma_f32_16x16x32_bf16 v[16:19], v[210:213], v[178:181], v[16:19]
	v_mfma_f32_16x16x32_bf16 v[12:15], v[202:205], v[186:189], v[12:15]
	v_mfma_f32_16x16x32_bf16 v[8:11], v[210:213], v[186:189], v[8:11]
	v_mfma_f32_16x16x32_bf16 v[4:7], v[202:205], v[194:197], v[4:7]
	v_mfma_f32_16x16x32_bf16 v[0:3], v[210:213], v[194:197], v[0:3]
	v_mfma_f32_16x16x32_bf16 v[28:31], v[206:209], v[166:169], v[28:31]
	v_mfma_f32_16x16x32_bf16 v[24:27], v[214:217], v[166:169], v[24:27]
	v_mfma_f32_16x16x32_bf16 v[20:23], v[206:209], v[182:185], v[20:23]
	v_mfma_f32_16x16x32_bf16 v[16:19], v[214:217], v[182:185], v[16:19]
	v_mfma_f32_16x16x32_bf16 v[12:15], v[206:209], v[190:193], v[12:15]
	v_mfma_f32_16x16x32_bf16 v[8:11], v[214:217], v[190:193], v[8:11]
	v_mfma_f32_16x16x32_bf16 v[4:7], v[206:209], v[198:201], v[4:7]
	v_mfma_f32_16x16x32_bf16 v[0:3], v[214:217], v[198:201], v[0:3]
	s_setprio 0
	s_add_i32 s61, s61, 2
	s_add_u32 s59, s59, 0x100
	s_addc_u32 s60, s60, 0
	s_add_u32 s8, s8, 0x100
	s_addc_u32 s9, s9, 0
	s_cmp_gt_u32 s61, 5
	s_barrier
	s_cbranch_scc0 .LBB0_1177
	s_lshl_b32 s8, s6, 8
	v_add_u32_e32 v158, s8, v160
	v_lshl_or_b32 v159, s7, 8, v162
	v_lshlrev_b32_e32 v166, 10, v158
	v_lshl_add_u32 v166, v159, 1, v166
	global_load_dwordx2 v[178:179], v166, s[14:15]
	global_load_dwordx2 v[180:181], v166, s[14:15] offset:32
	global_load_dwordx2 v[182:183], v166, s[14:15] offset:256
	global_load_dwordx2 v[184:185], v166, s[14:15] offset:288
	v_add_u32_e32 v167, 0x4000, v166
	global_load_dwordx2 v[186:187], v167, s[14:15]
	global_load_dwordx2 v[188:189], v167, s[14:15] offset:32
	global_load_dwordx2 v[190:191], v167, s[14:15] offset:256
	global_load_dwordx2 v[192:193], v167, s[14:15] offset:288
	v_add_u32_e32 v167, 0x8000, v166
	global_load_dwordx2 v[194:195], v167, s[14:15]
	global_load_dwordx2 v[196:197], v167, s[14:15] offset:32
	global_load_dwordx2 v[198:199], v167, s[14:15] offset:256
	global_load_dwordx2 v[200:201], v167, s[14:15] offset:288
	v_add_u32_e32 v167, 0xc000, v166
	global_load_dwordx2 v[202:203], v167, s[14:15]
	global_load_dwordx2 v[204:205], v167, s[14:15] offset:32
	global_load_dwordx2 v[206:207], v167, s[14:15] offset:256
	global_load_dwordx2 v[208:209], v167, s[14:15] offset:288
	v_add_u32_e32 v167, 0x20000, v166
	global_load_dwordx2 v[210:211], v167, s[14:15]
	global_load_dwordx2 v[212:213], v167, s[14:15] offset:32
	global_load_dwordx2 v[214:215], v167, s[14:15] offset:256
	global_load_dwordx2 v[216:217], v167, s[14:15] offset:288
	v_add_u32_e32 v167, 0x24000, v166
	global_load_dwordx2 v[218:219], v167, s[14:15]
	global_load_dwordx2 v[220:221], v167, s[14:15] offset:32
	global_load_dwordx2 v[222:223], v167, s[14:15] offset:256
	global_load_dwordx2 v[224:225], v167, s[14:15] offset:288
	v_add_u32_e32 v167, 0x28000, v166
	global_load_dwordx2 v[226:227], v167, s[14:15]
	global_load_dwordx2 v[228:229], v167, s[14:15] offset:32
	global_load_dwordx2 v[230:231], v167, s[14:15] offset:256
	global_load_dwordx2 v[232:233], v167, s[14:15] offset:288
	v_add_u32_e32 v167, 0x2c000, v166
	global_load_dwordx2 v[150:151], v167, s[14:15]
	global_load_dwordx2 v[152:153], v167, s[14:15] offset:32
	global_load_dwordx2 v[154:155], v167, s[14:15] offset:256
	global_load_dwordx2 v[156:157], v167, s[14:15] offset:288
	v_lshlrev_b32_e32 v168, 11, v158
	v_lshl_add_u32 v168, v159, 1, v168
	v_bfe_u32 v169, v162, 2, 2
	v_lshl_add_u32 v168, v169, 3, v168
	v_add_u32_e32 v168, 0xc99c400, v168
	v_and_b32_e32 v158, 15, v160
	v_and_b32_e32 v159, 1, v169
	v_lshrrev_b32_e32 v166, 1, v169
	v_lshl_or_b32 v159, v159, 1, v166
	v_xor_b32_e32 v166, 2, v159
	v_lshl_add_u32 v159, v159, 4, v158
	v_lshl_add_u32 v166, v166, 4, v158
	v_lshlrev_b32_e32 v159, 2, v159
	v_lshlrev_b32_e32 v166, 2, v166
	v_and_b32_e32 v167, 1, v169
	v_cmp_eq_u32_e64 s[8:9], 1, v167
	v_cmp_lt_u32_e64 s[10:11], 1, v169
	s_waitcnt vmcnt(31)
	v_mul_f32_e32 v124, 0xbfb8aa3b, v124
	v_mul_f32_e32 v125, 0xbfb8aa3b, v125
	v_mul_f32_e32 v126, 0xbfb8aa3b, v126
	v_mul_f32_e32 v127, 0xbfb8aa3b, v127
	v_exp_f32_e32 v124, v124
	v_exp_f32_e32 v125, v125
	v_exp_f32_e32 v126, v126
	v_exp_f32_e32 v127, v127
	v_lshlrev_b32_e32 v158, 16, v178
	v_and_b32_e32 v178, 0xffff0000, v178
	v_pk_add_f32 v[124:125], v[124:125], 1.0 op_sel_hi:[1,0]
	v_pk_add_f32 v[126:127], v[126:127], 1.0 op_sel_hi:[1,0]
	v_lshlrev_b32_e32 v167, 16, v179
	v_and_b32_e32 v179, 0xffff0000, v179
	v_div_scale_f32 v140, s[6:7], v124, v124, v158
	v_div_scale_f32 v141, s[6:7], v125, v125, v178
	v_rcp_f32_e32 v144, v140
	v_rcp_f32_e32 v145, v141
	v_div_scale_f32 v142, vcc, v158, v124, v158
	v_div_scale_f32 v143, s[6:7], v178, v125, v178
	v_fma_f32 v146, -v140, v144, 1.0
	v_fma_f32 v147, -v141, v145, 1.0
	v_fmac_f32_e32 v144, v146, v144
	v_fmac_f32_e32 v145, v147, v145
	v_mul_f32_e32 v148, v142, v144
	v_mul_f32_e32 v149, v143, v145
	v_fma_f32 v146, -v140, v148, v142
	v_fma_f32 v147, -v141, v149, v143
	v_fmac_f32_e32 v148, v146, v144
	v_fmac_f32_e32 v149, v147, v145
	v_fma_f32 v146, -v140, v148, v142
	v_fma_f32 v147, -v141, v149, v143
	v_div_fmas_f32 v146, v146, v144, v148
	s_mov_b64 vcc, s[6:7]
	v_div_fixup_f32 v124, v146, v124, v158
	s_nop 1
	v_div_fmas_f32 v147, v147, v145, v149
	v_div_fixup_f32 v125, v147, v125, v178
	v_div_scale_f32 v140, s[6:7], v126, v126, v167
	v_div_scale_f32 v141, s[6:7], v127, v127, v179
	v_rcp_f32_e32 v144, v140
	v_rcp_f32_e32 v145, v141
	v_div_scale_f32 v142, vcc, v167, v126, v167
	v_div_scale_f32 v143, s[6:7], v179, v127, v179
	v_fma_f32 v146, -v140, v144, 1.0
	v_fma_f32 v147, -v141, v145, 1.0
	v_fmac_f32_e32 v144, v146, v144
	v_fmac_f32_e32 v145, v147, v145
	v_mul_f32_e32 v148, v142, v144
	v_mul_f32_e32 v149, v143, v145
	v_fma_f32 v146, -v140, v148, v142
	v_fma_f32 v147, -v141, v149, v143
	v_fmac_f32_e32 v148, v146, v144
	v_fmac_f32_e32 v149, v147, v145
	v_fma_f32 v146, -v140, v148, v142
	v_fma_f32 v147, -v141, v149, v143
	v_div_fmas_f32 v146, v146, v144, v148
	s_mov_b64 vcc, s[6:7]
	v_div_fixup_f32 v126, v146, v126, v167
	s_nop 1
	v_div_fmas_f32 v147, v147, v145, v149
	v_div_fixup_f32 v127, v147, v127, v179
	v_cvt_pk_bf16_f32 v124, v124, v125
	v_cvt_pk_bf16_f32 v125, v126, v127
	s_waitcnt vmcnt(30)
	v_mul_f32_e32 v120, 0xbfb8aa3b, v120
	v_mul_f32_e32 v121, 0xbfb8aa3b, v121
	v_mul_f32_e32 v122, 0xbfb8aa3b, v122
	v_mul_f32_e32 v123, 0xbfb8aa3b, v123
	v_exp_f32_e32 v120, v120
	v_exp_f32_e32 v121, v121
	v_exp_f32_e32 v122, v122
	v_exp_f32_e32 v123, v123
	v_lshlrev_b32_e32 v158, 16, v180
	v_and_b32_e32 v180, 0xffff0000, v180
	v_pk_add_f32 v[120:121], v[120:121], 1.0 op_sel_hi:[1,0]
	v_pk_add_f32 v[122:123], v[122:123], 1.0 op_sel_hi:[1,0]
	v_lshlrev_b32_e32 v167, 16, v181
	v_and_b32_e32 v181, 0xffff0000, v181
	v_div_scale_f32 v140, s[6:7], v120, v120, v158
	v_div_scale_f32 v141, s[6:7], v121, v121, v180
	v_rcp_f32_e32 v144, v140
	v_rcp_f32_e32 v145, v141
	v_div_scale_f32 v142, vcc, v158, v120, v158
	v_div_scale_f32 v143, s[6:7], v180, v121, v180
	v_fma_f32 v146, -v140, v144, 1.0
	v_fma_f32 v147, -v141, v145, 1.0
	v_fmac_f32_e32 v144, v146, v144
	v_fmac_f32_e32 v145, v147, v145
	v_mul_f32_e32 v148, v142, v144
	v_mul_f32_e32 v149, v143, v145
	v_fma_f32 v146, -v140, v148, v142
	v_fma_f32 v147, -v141, v149, v143
	v_fmac_f32_e32 v148, v146, v144
	v_fmac_f32_e32 v149, v147, v145
	v_fma_f32 v146, -v140, v148, v142
	v_fma_f32 v147, -v141, v149, v143
	v_div_fmas_f32 v146, v146, v144, v148
	s_mov_b64 vcc, s[6:7]
	v_div_fixup_f32 v120, v146, v120, v158
	s_nop 1
	v_div_fmas_f32 v147, v147, v145, v149
	v_div_fixup_f32 v121, v147, v121, v180
	v_div_scale_f32 v140, s[6:7], v122, v122, v167
	v_div_scale_f32 v141, s[6:7], v123, v123, v181
	v_rcp_f32_e32 v144, v140
	v_rcp_f32_e32 v145, v141
	v_div_scale_f32 v142, vcc, v167, v122, v167
	v_div_scale_f32 v143, s[6:7], v181, v123, v181
	v_fma_f32 v146, -v140, v144, 1.0
	v_fma_f32 v147, -v141, v145, 1.0
	v_fmac_f32_e32 v144, v146, v144
	v_fmac_f32_e32 v145, v147, v145
	v_mul_f32_e32 v148, v142, v144
	v_mul_f32_e32 v149, v143, v145
	v_fma_f32 v146, -v140, v148, v142
	v_fma_f32 v147, -v141, v149, v143
	v_fmac_f32_e32 v148, v146, v144
	v_fmac_f32_e32 v149, v147, v145
	v_fma_f32 v146, -v140, v148, v142
	v_fma_f32 v147, -v141, v149, v143
	v_div_fmas_f32 v146, v146, v144, v148
	s_mov_b64 vcc, s[6:7]
	v_div_fixup_f32 v122, v146, v122, v167
	s_nop 1
	v_div_fmas_f32 v147, v147, v145, v149
	v_div_fixup_f32 v123, v147, v123, v181
	v_cvt_pk_bf16_f32 v120, v120, v121
	v_cvt_pk_bf16_f32 v121, v122, v123
	v_cndmask_b32_e64 v126, v124, v120, s[8:9]
	v_cndmask_b32_e64 v127, v125, v121, s[8:9]
	v_cndmask_b32_e64 v122, v120, v124, s[8:9]
	v_cndmask_b32_e64 v123, v121, v125, s[8:9]
	ds_permute_b32 v124, v159, v126
	ds_permute_b32 v125, v159, v127
	ds_permute_b32 v120, v166, v122
	ds_permute_b32 v121, v166, v123
	s_waitcnt vmcnt(29)
	v_mul_f32_e32 v92, 0xbfb8aa3b, v92
	v_mul_f32_e32 v93, 0xbfb8aa3b, v93
	v_mul_f32_e32 v94, 0xbfb8aa3b, v94
	v_mul_f32_e32 v95, 0xbfb8aa3b, v95
	v_exp_f32_e32 v92, v92
	v_exp_f32_e32 v93, v93
	v_exp_f32_e32 v94, v94
	v_exp_f32_e32 v95, v95
	v_lshlrev_b32_e32 v158, 16, v182
	v_and_b32_e32 v182, 0xffff0000, v182
	v_pk_add_f32 v[92:93], v[92:93], 1.0 op_sel_hi:[1,0]
	v_pk_add_f32 v[94:95], v[94:95], 1.0 op_sel_hi:[1,0]
	v_lshlrev_b32_e32 v167, 16, v183
	v_and_b32_e32 v183, 0xffff0000, v183
	v_div_scale_f32 v140, s[6:7], v92, v92, v158
	v_div_scale_f32 v141, s[6:7], v93, v93, v182
	v_rcp_f32_e32 v144, v140
	v_rcp_f32_e32 v145, v141
	v_div_scale_f32 v142, vcc, v158, v92, v158
	v_div_scale_f32 v143, s[6:7], v182, v93, v182
	v_fma_f32 v146, -v140, v144, 1.0
	v_fma_f32 v147, -v141, v145, 1.0
	v_fmac_f32_e32 v144, v146, v144
	v_fmac_f32_e32 v145, v147, v145
	v_mul_f32_e32 v148, v142, v144
	v_mul_f32_e32 v149, v143, v145
	v_fma_f32 v146, -v140, v148, v142
	v_fma_f32 v147, -v141, v149, v143
	v_fmac_f32_e32 v148, v146, v144
	v_fmac_f32_e32 v149, v147, v145
	v_fma_f32 v146, -v140, v148, v142
	v_fma_f32 v147, -v141, v149, v143
	v_div_fmas_f32 v146, v146, v144, v148
	s_mov_b64 vcc, s[6:7]
	v_div_fixup_f32 v92, v146, v92, v158
	s_nop 1
	v_div_fmas_f32 v147, v147, v145, v149
	v_div_fixup_f32 v93, v147, v93, v182
	v_div_scale_f32 v140, s[6:7], v94, v94, v167
	v_div_scale_f32 v141, s[6:7], v95, v95, v183
	v_rcp_f32_e32 v144, v140
	v_rcp_f32_e32 v145, v141
	v_div_scale_f32 v142, vcc, v167, v94, v167
	v_div_scale_f32 v143, s[6:7], v183, v95, v183
	v_fma_f32 v146, -v140, v144, 1.0
	v_fma_f32 v147, -v141, v145, 1.0
	v_fmac_f32_e32 v144, v146, v144
	v_fmac_f32_e32 v145, v147, v145
	v_mul_f32_e32 v148, v142, v144
	v_mul_f32_e32 v149, v143, v145
	v_fma_f32 v146, -v140, v148, v142
	v_fma_f32 v147, -v141, v149, v143
	v_fmac_f32_e32 v148, v146, v144
	v_fmac_f32_e32 v149, v147, v145
	v_fma_f32 v146, -v140, v148, v142
	v_fma_f32 v147, -v141, v149, v143
	v_div_fmas_f32 v146, v146, v144, v148
	s_mov_b64 vcc, s[6:7]
	v_div_fixup_f32 v94, v146, v94, v167
	s_nop 1
	v_div_fmas_f32 v147, v147, v145, v149
	v_div_fixup_f32 v95, v147, v95, v183
	v_cvt_pk_bf16_f32 v92, v92, v93
	v_cvt_pk_bf16_f32 v93, v94, v95
	s_waitcnt vmcnt(28)
	v_mul_f32_e32 v88, 0xbfb8aa3b, v88
	v_mul_f32_e32 v89, 0xbfb8aa3b, v89
	v_mul_f32_e32 v90, 0xbfb8aa3b, v90
	v_mul_f32_e32 v91, 0xbfb8aa3b, v91
	v_exp_f32_e32 v88, v88
	v_exp_f32_e32 v89, v89
	v_exp_f32_e32 v90, v90
	v_exp_f32_e32 v91, v91
	v_lshlrev_b32_e32 v158, 16, v184
	v_and_b32_e32 v184, 0xffff0000, v184
	v_pk_add_f32 v[88:89], v[88:89], 1.0 op_sel_hi:[1,0]
	v_pk_add_f32 v[90:91], v[90:91], 1.0 op_sel_hi:[1,0]
	v_lshlrev_b32_e32 v167, 16, v185
	v_and_b32_e32 v185, 0xffff0000, v185
	v_div_scale_f32 v140, s[6:7], v88, v88, v158
	v_div_scale_f32 v141, s[6:7], v89, v89, v184
	v_rcp_f32_e32 v144, v140
	v_rcp_f32_e32 v145, v141
	v_div_scale_f32 v142, vcc, v158, v88, v158
	v_div_scale_f32 v143, s[6:7], v184, v89, v184
	v_fma_f32 v146, -v140, v144, 1.0
	v_fma_f32 v147, -v141, v145, 1.0
	v_fmac_f32_e32 v144, v146, v144
	v_fmac_f32_e32 v145, v147, v145
	v_mul_f32_e32 v148, v142, v144
	v_mul_f32_e32 v149, v143, v145
	v_fma_f32 v146, -v140, v148, v142
	v_fma_f32 v147, -v141, v149, v143
	v_fmac_f32_e32 v148, v146, v144
	v_fmac_f32_e32 v149, v147, v145
	v_fma_f32 v146, -v140, v148, v142
	v_fma_f32 v147, -v141, v149, v143
	v_div_fmas_f32 v146, v146, v144, v148
	s_mov_b64 vcc, s[6:7]
	v_div_fixup_f32 v88, v146, v88, v158
	s_nop 1
	v_div_fmas_f32 v147, v147, v145, v149
	v_div_fixup_f32 v89, v147, v89, v184
	v_div_scale_f32 v140, s[6:7], v90, v90, v167
	v_div_scale_f32 v141, s[6:7], v91, v91, v185
	v_rcp_f32_e32 v144, v140
	v_rcp_f32_e32 v145, v141
	v_div_scale_f32 v142, vcc, v167, v90, v167
	v_div_scale_f32 v143, s[6:7], v185, v91, v185
	v_fma_f32 v146, -v140, v144, 1.0
	v_fma_f32 v147, -v141, v145, 1.0
	v_fmac_f32_e32 v144, v146, v144
	v_fmac_f32_e32 v145, v147, v145
	v_mul_f32_e32 v148, v142, v144
	v_mul_f32_e32 v149, v143, v145
	v_fma_f32 v146, -v140, v148, v142
	v_fma_f32 v147, -v141, v149, v143
	v_fmac_f32_e32 v148, v146, v144
	v_fmac_f32_e32 v149, v147, v145
	v_fma_f32 v146, -v140, v148, v142
	v_fma_f32 v147, -v141, v149, v143
	v_div_fmas_f32 v146, v146, v144, v148
	s_mov_b64 vcc, s[6:7]
	v_div_fixup_f32 v90, v146, v90, v167
	s_nop 1
	v_div_fmas_f32 v147, v147, v145, v149
	v_div_fixup_f32 v91, v147, v91, v185
	v_cvt_pk_bf16_f32 v88, v88, v89
	v_cvt_pk_bf16_f32 v89, v90, v91
	v_cndmask_b32_e64 v94, v92, v88, s[8:9]
	v_cndmask_b32_e64 v95, v93, v89, s[8:9]
	v_cndmask_b32_e64 v90, v88, v92, s[8:9]
	v_cndmask_b32_e64 v91, v89, v93, s[8:9]
	ds_permute_b32 v92, v159, v94
	ds_permute_b32 v93, v159, v95
	ds_permute_b32 v88, v166, v90
	ds_permute_b32 v89, v166, v91
	s_waitcnt lgkmcnt(4)
	v_cndmask_b32_e64 v126, v120, v124, s[10:11]
	v_cndmask_b32_e64 v127, v121, v125, s[10:11]
	v_cndmask_b32_e64 v124, v124, v120, s[10:11]
	v_cndmask_b32_e64 v125, v125, v121, s[10:11]
	global_store_dwordx4 v168, v[124:127], s[12:13]
	s_waitcnt vmcnt(28)
	v_mul_f32_e32 v116, 0xbfb8aa3b, v116
	v_mul_f32_e32 v117, 0xbfb8aa3b, v117
	v_mul_f32_e32 v118, 0xbfb8aa3b, v118
	v_mul_f32_e32 v119, 0xbfb8aa3b, v119
	v_exp_f32_e32 v116, v116
	v_exp_f32_e32 v117, v117
	v_exp_f32_e32 v118, v118
	v_exp_f32_e32 v119, v119
	v_lshlrev_b32_e32 v158, 16, v186
	v_and_b32_e32 v186, 0xffff0000, v186
	v_pk_add_f32 v[116:117], v[116:117], 1.0 op_sel_hi:[1,0]
	v_pk_add_f32 v[118:119], v[118:119], 1.0 op_sel_hi:[1,0]
	v_lshlrev_b32_e32 v167, 16, v187
	v_and_b32_e32 v187, 0xffff0000, v187
	v_div_scale_f32 v140, s[6:7], v116, v116, v158
	v_div_scale_f32 v141, s[6:7], v117, v117, v186
	v_rcp_f32_e32 v144, v140
	v_rcp_f32_e32 v145, v141
	v_div_scale_f32 v142, vcc, v158, v116, v158
	v_div_scale_f32 v143, s[6:7], v186, v117, v186
	v_fma_f32 v146, -v140, v144, 1.0
	v_fma_f32 v147, -v141, v145, 1.0
	v_fmac_f32_e32 v144, v146, v144
	v_fmac_f32_e32 v145, v147, v145
	v_mul_f32_e32 v148, v142, v144
	v_mul_f32_e32 v149, v143, v145
	v_fma_f32 v146, -v140, v148, v142
	v_fma_f32 v147, -v141, v149, v143
	v_fmac_f32_e32 v148, v146, v144
	v_fmac_f32_e32 v149, v147, v145
	v_fma_f32 v146, -v140, v148, v142
	v_fma_f32 v147, -v141, v149, v143
	v_div_fmas_f32 v146, v146, v144, v148
	s_mov_b64 vcc, s[6:7]
	v_div_fixup_f32 v116, v146, v116, v158
	s_nop 1
	v_div_fmas_f32 v147, v147, v145, v149
	v_div_fixup_f32 v117, v147, v117, v186
	v_div_scale_f32 v140, s[6:7], v118, v118, v167
	v_div_scale_f32 v141, s[6:7], v119, v119, v187
	v_rcp_f32_e32 v144, v140
	v_rcp_f32_e32 v145, v141
	v_div_scale_f32 v142, vcc, v167, v118, v167
	v_div_scale_f32 v143, s[6:7], v187, v119, v187
	v_fma_f32 v146, -v140, v144, 1.0
	v_fma_f32 v147, -v141, v145, 1.0
	v_fmac_f32_e32 v144, v146, v144
	v_fmac_f32_e32 v145, v147, v145
	v_mul_f32_e32 v148, v142, v144
	v_mul_f32_e32 v149, v143, v145
	v_fma_f32 v146, -v140, v148, v142
	v_fma_f32 v147, -v141, v149, v143
	v_fmac_f32_e32 v148, v146, v144
	v_fmac_f32_e32 v149, v147, v145
	v_fma_f32 v146, -v140, v148, v142
	v_fma_f32 v147, -v141, v149, v143
	v_div_fmas_f32 v146, v146, v144, v148
	s_mov_b64 vcc, s[6:7]
	v_div_fixup_f32 v118, v146, v118, v167
	s_nop 1
	v_div_fmas_f32 v147, v147, v145, v149
	v_div_fixup_f32 v119, v147, v119, v187
	v_cvt_pk_bf16_f32 v116, v116, v117
	v_cvt_pk_bf16_f32 v117, v118, v119
	s_waitcnt vmcnt(27)
	v_mul_f32_e32 v112, 0xbfb8aa3b, v112
	v_mul_f32_e32 v113, 0xbfb8aa3b, v113
	v_mul_f32_e32 v114, 0xbfb8aa3b, v114
	v_mul_f32_e32 v115, 0xbfb8aa3b, v115
	v_exp_f32_e32 v112, v112
	v_exp_f32_e32 v113, v113
	v_exp_f32_e32 v114, v114
	v_exp_f32_e32 v115, v115
	v_lshlrev_b32_e32 v158, 16, v188
	v_and_b32_e32 v188, 0xffff0000, v188
	v_pk_add_f32 v[112:113], v[112:113], 1.0 op_sel_hi:[1,0]
	v_pk_add_f32 v[114:115], v[114:115], 1.0 op_sel_hi:[1,0]
	v_lshlrev_b32_e32 v167, 16, v189
	v_and_b32_e32 v189, 0xffff0000, v189
	v_div_scale_f32 v140, s[6:7], v112, v112, v158
	v_div_scale_f32 v141, s[6:7], v113, v113, v188
	v_rcp_f32_e32 v144, v140
	v_rcp_f32_e32 v145, v141
	v_div_scale_f32 v142, vcc, v158, v112, v158
	v_div_scale_f32 v143, s[6:7], v188, v113, v188
	v_fma_f32 v146, -v140, v144, 1.0
	v_fma_f32 v147, -v141, v145, 1.0
	v_fmac_f32_e32 v144, v146, v144
	v_fmac_f32_e32 v145, v147, v145
	v_mul_f32_e32 v148, v142, v144
	v_mul_f32_e32 v149, v143, v145
	v_fma_f32 v146, -v140, v148, v142
	v_fma_f32 v147, -v141, v149, v143
	v_fmac_f32_e32 v148, v146, v144
	v_fmac_f32_e32 v149, v147, v145
	v_fma_f32 v146, -v140, v148, v142
	v_fma_f32 v147, -v141, v149, v143
	v_div_fmas_f32 v146, v146, v144, v148
	s_mov_b64 vcc, s[6:7]
	v_div_fixup_f32 v112, v146, v112, v158
	s_nop 1
	v_div_fmas_f32 v147, v147, v145, v149
	v_div_fixup_f32 v113, v147, v113, v188
	v_div_scale_f32 v140, s[6:7], v114, v114, v167
	v_div_scale_f32 v141, s[6:7], v115, v115, v189
	v_rcp_f32_e32 v144, v140
	v_rcp_f32_e32 v145, v141
	v_div_scale_f32 v142, vcc, v167, v114, v167
	v_div_scale_f32 v143, s[6:7], v189, v115, v189
	v_fma_f32 v146, -v140, v144, 1.0
	v_fma_f32 v147, -v141, v145, 1.0
	v_fmac_f32_e32 v144, v146, v144
	v_fmac_f32_e32 v145, v147, v145
	v_mul_f32_e32 v148, v142, v144
	v_mul_f32_e32 v149, v143, v145
	v_fma_f32 v146, -v140, v148, v142
	v_fma_f32 v147, -v141, v149, v143
	v_fmac_f32_e32 v148, v146, v144
	v_fmac_f32_e32 v149, v147, v145
	v_fma_f32 v146, -v140, v148, v142
	v_fma_f32 v147, -v141, v149, v143
	v_div_fmas_f32 v146, v146, v144, v148
	s_mov_b64 vcc, s[6:7]
	v_div_fixup_f32 v114, v146, v114, v167
	s_nop 1
	v_div_fmas_f32 v147, v147, v145, v149
	v_div_fixup_f32 v115, v147, v115, v189
	v_cvt_pk_bf16_f32 v112, v112, v113
	v_cvt_pk_bf16_f32 v113, v114, v115
	v_cndmask_b32_e64 v118, v116, v112, s[8:9]
	v_cndmask_b32_e64 v119, v117, v113, s[8:9]
	v_cndmask_b32_e64 v114, v112, v116, s[8:9]
	v_cndmask_b32_e64 v115, v113, v117, s[8:9]
	ds_permute_b32 v116, v159, v118
	ds_permute_b32 v117, v159, v119
	ds_permute_b32 v112, v166, v114
	ds_permute_b32 v113, v166, v115
	s_waitcnt lgkmcnt(4)
	v_cndmask_b32_e64 v94, v88, v92, s[10:11]
	v_cndmask_b32_e64 v95, v89, v93, s[10:11]
	v_cndmask_b32_e64 v92, v92, v88, s[10:11]
	v_cndmask_b32_e64 v93, v93, v89, s[10:11]
	v_add_u32_e32 v169, 0x100, v168
	global_store_dwordx4 v169, v[92:95], s[12:13]
	s_waitcnt vmcnt(27)
	v_mul_f32_e32 v84, 0xbfb8aa3b, v84
	v_mul_f32_e32 v85, 0xbfb8aa3b, v85
	v_mul_f32_e32 v86, 0xbfb8aa3b, v86
	v_mul_f32_e32 v87, 0xbfb8aa3b, v87
	v_exp_f32_e32 v84, v84
	v_exp_f32_e32 v85, v85
	v_exp_f32_e32 v86, v86
	v_exp_f32_e32 v87, v87
	v_lshlrev_b32_e32 v158, 16, v190
	v_and_b32_e32 v190, 0xffff0000, v190
	v_pk_add_f32 v[84:85], v[84:85], 1.0 op_sel_hi:[1,0]
	v_pk_add_f32 v[86:87], v[86:87], 1.0 op_sel_hi:[1,0]
	v_lshlrev_b32_e32 v167, 16, v191
	v_and_b32_e32 v191, 0xffff0000, v191
	v_div_scale_f32 v140, s[6:7], v84, v84, v158
	v_div_scale_f32 v141, s[6:7], v85, v85, v190
	v_rcp_f32_e32 v144, v140
	v_rcp_f32_e32 v145, v141
	v_div_scale_f32 v142, vcc, v158, v84, v158
	v_div_scale_f32 v143, s[6:7], v190, v85, v190
	v_fma_f32 v146, -v140, v144, 1.0
	v_fma_f32 v147, -v141, v145, 1.0
	v_fmac_f32_e32 v144, v146, v144
	v_fmac_f32_e32 v145, v147, v145
	v_mul_f32_e32 v148, v142, v144
	v_mul_f32_e32 v149, v143, v145
	v_fma_f32 v146, -v140, v148, v142
	v_fma_f32 v147, -v141, v149, v143
	v_fmac_f32_e32 v148, v146, v144
	v_fmac_f32_e32 v149, v147, v145
	v_fma_f32 v146, -v140, v148, v142
	v_fma_f32 v147, -v141, v149, v143
	v_div_fmas_f32 v146, v146, v144, v148
	s_mov_b64 vcc, s[6:7]
	v_div_fixup_f32 v84, v146, v84, v158
	s_nop 1
	v_div_fmas_f32 v147, v147, v145, v149
	v_div_fixup_f32 v85, v147, v85, v190
	v_div_scale_f32 v140, s[6:7], v86, v86, v167
	v_div_scale_f32 v141, s[6:7], v87, v87, v191
	v_rcp_f32_e32 v144, v140
	v_rcp_f32_e32 v145, v141
	v_div_scale_f32 v142, vcc, v167, v86, v167
	v_div_scale_f32 v143, s[6:7], v191, v87, v191
	v_fma_f32 v146, -v140, v144, 1.0
	v_fma_f32 v147, -v141, v145, 1.0
	v_fmac_f32_e32 v144, v146, v144
	v_fmac_f32_e32 v145, v147, v145
	v_mul_f32_e32 v148, v142, v144
	v_mul_f32_e32 v149, v143, v145
	v_fma_f32 v146, -v140, v148, v142
	v_fma_f32 v147, -v141, v149, v143
	v_fmac_f32_e32 v148, v146, v144
	v_fmac_f32_e32 v149, v147, v145
	v_fma_f32 v146, -v140, v148, v142
	v_fma_f32 v147, -v141, v149, v143
	v_div_fmas_f32 v146, v146, v144, v148
	s_mov_b64 vcc, s[6:7]
	v_div_fixup_f32 v86, v146, v86, v167
	s_nop 1
	v_div_fmas_f32 v147, v147, v145, v149
	v_div_fixup_f32 v87, v147, v87, v191
	v_cvt_pk_bf16_f32 v84, v84, v85
	v_cvt_pk_bf16_f32 v85, v86, v87
	s_waitcnt vmcnt(26)
	v_mul_f32_e32 v80, 0xbfb8aa3b, v80
	v_mul_f32_e32 v81, 0xbfb8aa3b, v81
	v_mul_f32_e32 v82, 0xbfb8aa3b, v82
	v_mul_f32_e32 v83, 0xbfb8aa3b, v83
	v_exp_f32_e32 v80, v80
	v_exp_f32_e32 v81, v81
	v_exp_f32_e32 v82, v82
	v_exp_f32_e32 v83, v83
	v_lshlrev_b32_e32 v158, 16, v192
	v_and_b32_e32 v192, 0xffff0000, v192
	v_pk_add_f32 v[80:81], v[80:81], 1.0 op_sel_hi:[1,0]
	v_pk_add_f32 v[82:83], v[82:83], 1.0 op_sel_hi:[1,0]
	v_lshlrev_b32_e32 v167, 16, v193
	v_and_b32_e32 v193, 0xffff0000, v193
	v_div_scale_f32 v140, s[6:7], v80, v80, v158
	v_div_scale_f32 v141, s[6:7], v81, v81, v192
	v_rcp_f32_e32 v144, v140
	v_rcp_f32_e32 v145, v141
	v_div_scale_f32 v142, vcc, v158, v80, v158
	v_div_scale_f32 v143, s[6:7], v192, v81, v192
	v_fma_f32 v146, -v140, v144, 1.0
	v_fma_f32 v147, -v141, v145, 1.0
	v_fmac_f32_e32 v144, v146, v144
	v_fmac_f32_e32 v145, v147, v145
	v_mul_f32_e32 v148, v142, v144
	v_mul_f32_e32 v149, v143, v145
	v_fma_f32 v146, -v140, v148, v142
	v_fma_f32 v147, -v141, v149, v143
	v_fmac_f32_e32 v148, v146, v144
	v_fmac_f32_e32 v149, v147, v145
	v_fma_f32 v146, -v140, v148, v142
	v_fma_f32 v147, -v141, v149, v143
	v_div_fmas_f32 v146, v146, v144, v148
	s_mov_b64 vcc, s[6:7]
	v_div_fixup_f32 v80, v146, v80, v158
	s_nop 1
	v_div_fmas_f32 v147, v147, v145, v149
	v_div_fixup_f32 v81, v147, v81, v192
	v_div_scale_f32 v140, s[6:7], v82, v82, v167
	v_div_scale_f32 v141, s[6:7], v83, v83, v193
	v_rcp_f32_e32 v144, v140
	v_rcp_f32_e32 v145, v141
	v_div_scale_f32 v142, vcc, v167, v82, v167
	v_div_scale_f32 v143, s[6:7], v193, v83, v193
	v_fma_f32 v146, -v140, v144, 1.0
	v_fma_f32 v147, -v141, v145, 1.0
	v_fmac_f32_e32 v144, v146, v144
	v_fmac_f32_e32 v145, v147, v145
	v_mul_f32_e32 v148, v142, v144
	v_mul_f32_e32 v149, v143, v145
	v_fma_f32 v146, -v140, v148, v142
	v_fma_f32 v147, -v141, v149, v143
	v_fmac_f32_e32 v148, v146, v144
	v_fmac_f32_e32 v149, v147, v145
	v_fma_f32 v146, -v140, v148, v142
	v_fma_f32 v147, -v141, v149, v143
	v_div_fmas_f32 v146, v146, v144, v148
	s_mov_b64 vcc, s[6:7]
	v_div_fixup_f32 v82, v146, v82, v167
	s_nop 1
	v_div_fmas_f32 v147, v147, v145, v149
	v_div_fixup_f32 v83, v147, v83, v193
	v_cvt_pk_bf16_f32 v80, v80, v81
	v_cvt_pk_bf16_f32 v81, v82, v83
	v_cndmask_b32_e64 v86, v84, v80, s[8:9]
	v_cndmask_b32_e64 v87, v85, v81, s[8:9]
	v_cndmask_b32_e64 v82, v80, v84, s[8:9]
	v_cndmask_b32_e64 v83, v81, v85, s[8:9]
	ds_permute_b32 v84, v159, v86
	ds_permute_b32 v85, v159, v87
	ds_permute_b32 v80, v166, v82
	ds_permute_b32 v81, v166, v83
	s_waitcnt lgkmcnt(4)
	v_cndmask_b32_e64 v118, v112, v116, s[10:11]
	v_cndmask_b32_e64 v119, v113, v117, s[10:11]
	v_cndmask_b32_e64 v116, v116, v112, s[10:11]
	v_cndmask_b32_e64 v117, v117, v113, s[10:11]
	v_add_u32_e32 v169, 0x8000, v168
	global_store_dwordx4 v169, v[116:119], s[12:13]
	s_waitcnt vmcnt(26)
	v_mul_f32_e32 v108, 0xbfb8aa3b, v108
	v_mul_f32_e32 v109, 0xbfb8aa3b, v109
	v_mul_f32_e32 v110, 0xbfb8aa3b, v110
	v_mul_f32_e32 v111, 0xbfb8aa3b, v111
	v_exp_f32_e32 v108, v108
	v_exp_f32_e32 v109, v109
	v_exp_f32_e32 v110, v110
	v_exp_f32_e32 v111, v111
	v_lshlrev_b32_e32 v158, 16, v194
	v_and_b32_e32 v194, 0xffff0000, v194
	v_pk_add_f32 v[108:109], v[108:109], 1.0 op_sel_hi:[1,0]
	v_pk_add_f32 v[110:111], v[110:111], 1.0 op_sel_hi:[1,0]
	v_lshlrev_b32_e32 v167, 16, v195
	v_and_b32_e32 v195, 0xffff0000, v195
	v_div_scale_f32 v140, s[6:7], v108, v108, v158
	v_div_scale_f32 v141, s[6:7], v109, v109, v194
	v_rcp_f32_e32 v144, v140
	v_rcp_f32_e32 v145, v141
	v_div_scale_f32 v142, vcc, v158, v108, v158
	v_div_scale_f32 v143, s[6:7], v194, v109, v194
	v_fma_f32 v146, -v140, v144, 1.0
	v_fma_f32 v147, -v141, v145, 1.0
	v_fmac_f32_e32 v144, v146, v144
	v_fmac_f32_e32 v145, v147, v145
	v_mul_f32_e32 v148, v142, v144
	v_mul_f32_e32 v149, v143, v145
	v_fma_f32 v146, -v140, v148, v142
	v_fma_f32 v147, -v141, v149, v143
	v_fmac_f32_e32 v148, v146, v144
	v_fmac_f32_e32 v149, v147, v145
	v_fma_f32 v146, -v140, v148, v142
	v_fma_f32 v147, -v141, v149, v143
	v_div_fmas_f32 v146, v146, v144, v148
	s_mov_b64 vcc, s[6:7]
	v_div_fixup_f32 v108, v146, v108, v158
	s_nop 1
	v_div_fmas_f32 v147, v147, v145, v149
	v_div_fixup_f32 v109, v147, v109, v194
	v_div_scale_f32 v140, s[6:7], v110, v110, v167
	v_div_scale_f32 v141, s[6:7], v111, v111, v195
	v_rcp_f32_e32 v144, v140
	v_rcp_f32_e32 v145, v141
	v_div_scale_f32 v142, vcc, v167, v110, v167
	v_div_scale_f32 v143, s[6:7], v195, v111, v195
	v_fma_f32 v146, -v140, v144, 1.0
	v_fma_f32 v147, -v141, v145, 1.0
	v_fmac_f32_e32 v144, v146, v144
	v_fmac_f32_e32 v145, v147, v145
	v_mul_f32_e32 v148, v142, v144
	v_mul_f32_e32 v149, v143, v145
	v_fma_f32 v146, -v140, v148, v142
	v_fma_f32 v147, -v141, v149, v143
	v_fmac_f32_e32 v148, v146, v144
	v_fmac_f32_e32 v149, v147, v145
	v_fma_f32 v146, -v140, v148, v142
	v_fma_f32 v147, -v141, v149, v143
	v_div_fmas_f32 v146, v146, v144, v148
	s_mov_b64 vcc, s[6:7]
	v_div_fixup_f32 v110, v146, v110, v167
	s_nop 1
	v_div_fmas_f32 v147, v147, v145, v149
	v_div_fixup_f32 v111, v147, v111, v195
	v_cvt_pk_bf16_f32 v108, v108, v109
	v_cvt_pk_bf16_f32 v109, v110, v111
	s_waitcnt vmcnt(25)
	v_mul_f32_e32 v104, 0xbfb8aa3b, v104
	v_mul_f32_e32 v105, 0xbfb8aa3b, v105
	v_mul_f32_e32 v106, 0xbfb8aa3b, v106
	v_mul_f32_e32 v107, 0xbfb8aa3b, v107
	v_exp_f32_e32 v104, v104
	v_exp_f32_e32 v105, v105
	v_exp_f32_e32 v106, v106
	v_exp_f32_e32 v107, v107
	v_lshlrev_b32_e32 v158, 16, v196
	v_and_b32_e32 v196, 0xffff0000, v196
	v_pk_add_f32 v[104:105], v[104:105], 1.0 op_sel_hi:[1,0]
	v_pk_add_f32 v[106:107], v[106:107], 1.0 op_sel_hi:[1,0]
	v_lshlrev_b32_e32 v167, 16, v197
	v_and_b32_e32 v197, 0xffff0000, v197
	v_div_scale_f32 v140, s[6:7], v104, v104, v158
	v_div_scale_f32 v141, s[6:7], v105, v105, v196
	v_rcp_f32_e32 v144, v140
	v_rcp_f32_e32 v145, v141
	v_div_scale_f32 v142, vcc, v158, v104, v158
	v_div_scale_f32 v143, s[6:7], v196, v105, v196
	v_fma_f32 v146, -v140, v144, 1.0
	v_fma_f32 v147, -v141, v145, 1.0
	v_fmac_f32_e32 v144, v146, v144
	v_fmac_f32_e32 v145, v147, v145
	v_mul_f32_e32 v148, v142, v144
	v_mul_f32_e32 v149, v143, v145
	v_fma_f32 v146, -v140, v148, v142
	v_fma_f32 v147, -v141, v149, v143
	v_fmac_f32_e32 v148, v146, v144
	v_fmac_f32_e32 v149, v147, v145
	v_fma_f32 v146, -v140, v148, v142
	v_fma_f32 v147, -v141, v149, v143
	v_div_fmas_f32 v146, v146, v144, v148
	s_mov_b64 vcc, s[6:7]
	v_div_fixup_f32 v104, v146, v104, v158
	s_nop 1
	v_div_fmas_f32 v147, v147, v145, v149
	v_div_fixup_f32 v105, v147, v105, v196
	v_div_scale_f32 v140, s[6:7], v106, v106, v167
	v_div_scale_f32 v141, s[6:7], v107, v107, v197
	v_rcp_f32_e32 v144, v140
	v_rcp_f32_e32 v145, v141
	v_div_scale_f32 v142, vcc, v167, v106, v167
	v_div_scale_f32 v143, s[6:7], v197, v107, v197
	v_fma_f32 v146, -v140, v144, 1.0
	v_fma_f32 v147, -v141, v145, 1.0
	v_fmac_f32_e32 v144, v146, v144
	v_fmac_f32_e32 v145, v147, v145
	v_mul_f32_e32 v148, v142, v144
	v_mul_f32_e32 v149, v143, v145
	v_fma_f32 v146, -v140, v148, v142
	v_fma_f32 v147, -v141, v149, v143
	v_fmac_f32_e32 v148, v146, v144
	v_fmac_f32_e32 v149, v147, v145
	v_fma_f32 v146, -v140, v148, v142
	v_fma_f32 v147, -v141, v149, v143
	v_div_fmas_f32 v146, v146, v144, v148
	s_mov_b64 vcc, s[6:7]
	v_div_fixup_f32 v106, v146, v106, v167
	s_nop 1
	v_div_fmas_f32 v147, v147, v145, v149
	v_div_fixup_f32 v107, v147, v107, v197
	v_cvt_pk_bf16_f32 v104, v104, v105
	v_cvt_pk_bf16_f32 v105, v106, v107
	v_cndmask_b32_e64 v110, v108, v104, s[8:9]
	v_cndmask_b32_e64 v111, v109, v105, s[8:9]
	v_cndmask_b32_e64 v106, v104, v108, s[8:9]
	v_cndmask_b32_e64 v107, v105, v109, s[8:9]
	ds_permute_b32 v108, v159, v110
	ds_permute_b32 v109, v159, v111
	ds_permute_b32 v104, v166, v106
	ds_permute_b32 v105, v166, v107
	s_waitcnt lgkmcnt(4)
	v_cndmask_b32_e64 v86, v80, v84, s[10:11]
	v_cndmask_b32_e64 v87, v81, v85, s[10:11]
	v_cndmask_b32_e64 v84, v84, v80, s[10:11]
	v_cndmask_b32_e64 v85, v85, v81, s[10:11]
	v_add_u32_e32 v169, 0x8100, v168
	global_store_dwordx4 v169, v[84:87], s[12:13]
	s_waitcnt vmcnt(25)
	v_mul_f32_e32 v76, 0xbfb8aa3b, v76
	v_mul_f32_e32 v77, 0xbfb8aa3b, v77
	v_mul_f32_e32 v78, 0xbfb8aa3b, v78
	v_mul_f32_e32 v79, 0xbfb8aa3b, v79
	v_exp_f32_e32 v76, v76
	v_exp_f32_e32 v77, v77
	v_exp_f32_e32 v78, v78
	v_exp_f32_e32 v79, v79
	v_lshlrev_b32_e32 v158, 16, v198
	v_and_b32_e32 v198, 0xffff0000, v198
	v_pk_add_f32 v[76:77], v[76:77], 1.0 op_sel_hi:[1,0]
	v_pk_add_f32 v[78:79], v[78:79], 1.0 op_sel_hi:[1,0]
	v_lshlrev_b32_e32 v167, 16, v199
	v_and_b32_e32 v199, 0xffff0000, v199
	v_div_scale_f32 v140, s[6:7], v76, v76, v158
	v_div_scale_f32 v141, s[6:7], v77, v77, v198
	v_rcp_f32_e32 v144, v140
	v_rcp_f32_e32 v145, v141
	v_div_scale_f32 v142, vcc, v158, v76, v158
	v_div_scale_f32 v143, s[6:7], v198, v77, v198
	v_fma_f32 v146, -v140, v144, 1.0
	v_fma_f32 v147, -v141, v145, 1.0
	v_fmac_f32_e32 v144, v146, v144
	v_fmac_f32_e32 v145, v147, v145
	v_mul_f32_e32 v148, v142, v144
	v_mul_f32_e32 v149, v143, v145
	v_fma_f32 v146, -v140, v148, v142
	v_fma_f32 v147, -v141, v149, v143
	v_fmac_f32_e32 v148, v146, v144
	v_fmac_f32_e32 v149, v147, v145
	v_fma_f32 v146, -v140, v148, v142
	v_fma_f32 v147, -v141, v149, v143
	v_div_fmas_f32 v146, v146, v144, v148
	s_mov_b64 vcc, s[6:7]
	v_div_fixup_f32 v76, v146, v76, v158
	s_nop 1
	v_div_fmas_f32 v147, v147, v145, v149
	v_div_fixup_f32 v77, v147, v77, v198
	v_div_scale_f32 v140, s[6:7], v78, v78, v167
	v_div_scale_f32 v141, s[6:7], v79, v79, v199
	v_rcp_f32_e32 v144, v140
	v_rcp_f32_e32 v145, v141
	v_div_scale_f32 v142, vcc, v167, v78, v167
	v_div_scale_f32 v143, s[6:7], v199, v79, v199
	v_fma_f32 v146, -v140, v144, 1.0
	v_fma_f32 v147, -v141, v145, 1.0
	v_fmac_f32_e32 v144, v146, v144
	v_fmac_f32_e32 v145, v147, v145
	v_mul_f32_e32 v148, v142, v144
	v_mul_f32_e32 v149, v143, v145
	v_fma_f32 v146, -v140, v148, v142
	v_fma_f32 v147, -v141, v149, v143
	v_fmac_f32_e32 v148, v146, v144
	v_fmac_f32_e32 v149, v147, v145
	v_fma_f32 v146, -v140, v148, v142
	v_fma_f32 v147, -v141, v149, v143
	v_div_fmas_f32 v146, v146, v144, v148
	s_mov_b64 vcc, s[6:7]
	v_div_fixup_f32 v78, v146, v78, v167
	s_nop 1
	v_div_fmas_f32 v147, v147, v145, v149
	v_div_fixup_f32 v79, v147, v79, v199
	v_cvt_pk_bf16_f32 v76, v76, v77
	v_cvt_pk_bf16_f32 v77, v78, v79
	s_waitcnt vmcnt(24)
	v_mul_f32_e32 v72, 0xbfb8aa3b, v72
	v_mul_f32_e32 v73, 0xbfb8aa3b, v73
	v_mul_f32_e32 v74, 0xbfb8aa3b, v74
	v_mul_f32_e32 v75, 0xbfb8aa3b, v75
	v_exp_f32_e32 v72, v72
	v_exp_f32_e32 v73, v73
	v_exp_f32_e32 v74, v74
	v_exp_f32_e32 v75, v75
	v_lshlrev_b32_e32 v158, 16, v200
	v_and_b32_e32 v200, 0xffff0000, v200
	v_pk_add_f32 v[72:73], v[72:73], 1.0 op_sel_hi:[1,0]
	v_pk_add_f32 v[74:75], v[74:75], 1.0 op_sel_hi:[1,0]
	v_lshlrev_b32_e32 v167, 16, v201
	v_and_b32_e32 v201, 0xffff0000, v201
	v_div_scale_f32 v140, s[6:7], v72, v72, v158
	v_div_scale_f32 v141, s[6:7], v73, v73, v200
	v_rcp_f32_e32 v144, v140
	v_rcp_f32_e32 v145, v141
	v_div_scale_f32 v142, vcc, v158, v72, v158
	v_div_scale_f32 v143, s[6:7], v200, v73, v200
	v_fma_f32 v146, -v140, v144, 1.0
	v_fma_f32 v147, -v141, v145, 1.0
	v_fmac_f32_e32 v144, v146, v144
	v_fmac_f32_e32 v145, v147, v145
	v_mul_f32_e32 v148, v142, v144
	v_mul_f32_e32 v149, v143, v145
	v_fma_f32 v146, -v140, v148, v142
	v_fma_f32 v147, -v141, v149, v143
	v_fmac_f32_e32 v148, v146, v144
	v_fmac_f32_e32 v149, v147, v145
	v_fma_f32 v146, -v140, v148, v142
	v_fma_f32 v147, -v141, v149, v143
	v_div_fmas_f32 v146, v146, v144, v148
	s_mov_b64 vcc, s[6:7]
	v_div_fixup_f32 v72, v146, v72, v158
	s_nop 1
	v_div_fmas_f32 v147, v147, v145, v149
	v_div_fixup_f32 v73, v147, v73, v200
	v_div_scale_f32 v140, s[6:7], v74, v74, v167
	v_div_scale_f32 v141, s[6:7], v75, v75, v201
	v_rcp_f32_e32 v144, v140
	v_rcp_f32_e32 v145, v141
	v_div_scale_f32 v142, vcc, v167, v74, v167
	v_div_scale_f32 v143, s[6:7], v201, v75, v201
	v_fma_f32 v146, -v140, v144, 1.0
	v_fma_f32 v147, -v141, v145, 1.0
	v_fmac_f32_e32 v144, v146, v144
	v_fmac_f32_e32 v145, v147, v145
	v_mul_f32_e32 v148, v142, v144
	v_mul_f32_e32 v149, v143, v145
	v_fma_f32 v146, -v140, v148, v142
	v_fma_f32 v147, -v141, v149, v143
	v_fmac_f32_e32 v148, v146, v144
	v_fmac_f32_e32 v149, v147, v145
	v_fma_f32 v146, -v140, v148, v142
	v_fma_f32 v147, -v141, v149, v143
	v_div_fmas_f32 v146, v146, v144, v148
	s_mov_b64 vcc, s[6:7]
	v_div_fixup_f32 v74, v146, v74, v167
	s_nop 1
	v_div_fmas_f32 v147, v147, v145, v149
	v_div_fixup_f32 v75, v147, v75, v201
	v_cvt_pk_bf16_f32 v72, v72, v73
	v_cvt_pk_bf16_f32 v73, v74, v75
	v_cndmask_b32_e64 v78, v76, v72, s[8:9]
	v_cndmask_b32_e64 v79, v77, v73, s[8:9]
	v_cndmask_b32_e64 v74, v72, v76, s[8:9]
	v_cndmask_b32_e64 v75, v73, v77, s[8:9]
	ds_permute_b32 v76, v159, v78
	ds_permute_b32 v77, v159, v79
	ds_permute_b32 v72, v166, v74
	ds_permute_b32 v73, v166, v75
	s_waitcnt lgkmcnt(4)
	v_cndmask_b32_e64 v110, v104, v108, s[10:11]
	v_cndmask_b32_e64 v111, v105, v109, s[10:11]
	v_cndmask_b32_e64 v108, v108, v104, s[10:11]
	v_cndmask_b32_e64 v109, v109, v105, s[10:11]
	v_add_u32_e32 v169, 0x10000, v168
	global_store_dwordx4 v169, v[108:111], s[12:13]
	s_waitcnt vmcnt(24)
	v_mul_f32_e32 v100, 0xbfb8aa3b, v100
	v_mul_f32_e32 v101, 0xbfb8aa3b, v101
	v_mul_f32_e32 v102, 0xbfb8aa3b, v102
	v_mul_f32_e32 v103, 0xbfb8aa3b, v103
	v_exp_f32_e32 v100, v100
	v_exp_f32_e32 v101, v101
	v_exp_f32_e32 v102, v102
	v_exp_f32_e32 v103, v103
	v_lshlrev_b32_e32 v158, 16, v202
	v_and_b32_e32 v202, 0xffff0000, v202
	v_pk_add_f32 v[100:101], v[100:101], 1.0 op_sel_hi:[1,0]
	v_pk_add_f32 v[102:103], v[102:103], 1.0 op_sel_hi:[1,0]
	v_lshlrev_b32_e32 v167, 16, v203
	v_and_b32_e32 v203, 0xffff0000, v203
	v_div_scale_f32 v140, s[6:7], v100, v100, v158
	v_div_scale_f32 v141, s[6:7], v101, v101, v202
	v_rcp_f32_e32 v144, v140
	v_rcp_f32_e32 v145, v141
	v_div_scale_f32 v142, vcc, v158, v100, v158
	v_div_scale_f32 v143, s[6:7], v202, v101, v202
	v_fma_f32 v146, -v140, v144, 1.0
	v_fma_f32 v147, -v141, v145, 1.0
	v_fmac_f32_e32 v144, v146, v144
	v_fmac_f32_e32 v145, v147, v145
	v_mul_f32_e32 v148, v142, v144
	v_mul_f32_e32 v149, v143, v145
	v_fma_f32 v146, -v140, v148, v142
	v_fma_f32 v147, -v141, v149, v143
	v_fmac_f32_e32 v148, v146, v144
	v_fmac_f32_e32 v149, v147, v145
	v_fma_f32 v146, -v140, v148, v142
	v_fma_f32 v147, -v141, v149, v143
	v_div_fmas_f32 v146, v146, v144, v148
	s_mov_b64 vcc, s[6:7]
	v_div_fixup_f32 v100, v146, v100, v158
	s_nop 1
	v_div_fmas_f32 v147, v147, v145, v149
	v_div_fixup_f32 v101, v147, v101, v202
	v_div_scale_f32 v140, s[6:7], v102, v102, v167
	v_div_scale_f32 v141, s[6:7], v103, v103, v203
	v_rcp_f32_e32 v144, v140
	v_rcp_f32_e32 v145, v141
	v_div_scale_f32 v142, vcc, v167, v102, v167
	v_div_scale_f32 v143, s[6:7], v203, v103, v203
	v_fma_f32 v146, -v140, v144, 1.0
	v_fma_f32 v147, -v141, v145, 1.0
	v_fmac_f32_e32 v144, v146, v144
	v_fmac_f32_e32 v145, v147, v145
	v_mul_f32_e32 v148, v142, v144
	v_mul_f32_e32 v149, v143, v145
	v_fma_f32 v146, -v140, v148, v142
	v_fma_f32 v147, -v141, v149, v143
	v_fmac_f32_e32 v148, v146, v144
	v_fmac_f32_e32 v149, v147, v145
	v_fma_f32 v146, -v140, v148, v142
	v_fma_f32 v147, -v141, v149, v143
	v_div_fmas_f32 v146, v146, v144, v148
	s_mov_b64 vcc, s[6:7]
	v_div_fixup_f32 v102, v146, v102, v167
	s_nop 1
	v_div_fmas_f32 v147, v147, v145, v149
	v_div_fixup_f32 v103, v147, v103, v203
	v_cvt_pk_bf16_f32 v100, v100, v101
	v_cvt_pk_bf16_f32 v101, v102, v103
	s_waitcnt vmcnt(23)
	v_mul_f32_e32 v96, 0xbfb8aa3b, v96
	v_mul_f32_e32 v97, 0xbfb8aa3b, v97
	v_mul_f32_e32 v98, 0xbfb8aa3b, v98
	v_mul_f32_e32 v99, 0xbfb8aa3b, v99
	v_exp_f32_e32 v96, v96
	v_exp_f32_e32 v97, v97
	v_exp_f32_e32 v98, v98
	v_exp_f32_e32 v99, v99
	v_lshlrev_b32_e32 v158, 16, v204
	v_and_b32_e32 v204, 0xffff0000, v204
	v_pk_add_f32 v[96:97], v[96:97], 1.0 op_sel_hi:[1,0]
	v_pk_add_f32 v[98:99], v[98:99], 1.0 op_sel_hi:[1,0]
	v_lshlrev_b32_e32 v167, 16, v205
	v_and_b32_e32 v205, 0xffff0000, v205
	v_div_scale_f32 v140, s[6:7], v96, v96, v158
	v_div_scale_f32 v141, s[6:7], v97, v97, v204
	v_rcp_f32_e32 v144, v140
	v_rcp_f32_e32 v145, v141
	v_div_scale_f32 v142, vcc, v158, v96, v158
	v_div_scale_f32 v143, s[6:7], v204, v97, v204
	v_fma_f32 v146, -v140, v144, 1.0
	v_fma_f32 v147, -v141, v145, 1.0
	v_fmac_f32_e32 v144, v146, v144
	v_fmac_f32_e32 v145, v147, v145
	v_mul_f32_e32 v148, v142, v144
	v_mul_f32_e32 v149, v143, v145
	v_fma_f32 v146, -v140, v148, v142
	v_fma_f32 v147, -v141, v149, v143
	v_fmac_f32_e32 v148, v146, v144
	v_fmac_f32_e32 v149, v147, v145
	v_fma_f32 v146, -v140, v148, v142
	v_fma_f32 v147, -v141, v149, v143
	v_div_fmas_f32 v146, v146, v144, v148
	s_mov_b64 vcc, s[6:7]
	v_div_fixup_f32 v96, v146, v96, v158
	s_nop 1
	v_div_fmas_f32 v147, v147, v145, v149
	v_div_fixup_f32 v97, v147, v97, v204
	v_div_scale_f32 v140, s[6:7], v98, v98, v167
	v_div_scale_f32 v141, s[6:7], v99, v99, v205
	v_rcp_f32_e32 v144, v140
	v_rcp_f32_e32 v145, v141
	v_div_scale_f32 v142, vcc, v167, v98, v167
	v_div_scale_f32 v143, s[6:7], v205, v99, v205
	v_fma_f32 v146, -v140, v144, 1.0
	v_fma_f32 v147, -v141, v145, 1.0
	v_fmac_f32_e32 v144, v146, v144
	v_fmac_f32_e32 v145, v147, v145
	v_mul_f32_e32 v148, v142, v144
	v_mul_f32_e32 v149, v143, v145
	v_fma_f32 v146, -v140, v148, v142
	v_fma_f32 v147, -v141, v149, v143
	v_fmac_f32_e32 v148, v146, v144
	v_fmac_f32_e32 v149, v147, v145
	v_fma_f32 v146, -v140, v148, v142
	v_fma_f32 v147, -v141, v149, v143
	v_div_fmas_f32 v146, v146, v144, v148
	s_mov_b64 vcc, s[6:7]
	v_div_fixup_f32 v98, v146, v98, v167
	s_nop 1
	v_div_fmas_f32 v147, v147, v145, v149
	v_div_fixup_f32 v99, v147, v99, v205
	v_cvt_pk_bf16_f32 v96, v96, v97
	v_cvt_pk_bf16_f32 v97, v98, v99
	v_cndmask_b32_e64 v102, v100, v96, s[8:9]
	v_cndmask_b32_e64 v103, v101, v97, s[8:9]
	v_cndmask_b32_e64 v98, v96, v100, s[8:9]
	v_cndmask_b32_e64 v99, v97, v101, s[8:9]
	ds_permute_b32 v100, v159, v102
	ds_permute_b32 v101, v159, v103
	ds_permute_b32 v96, v166, v98
	ds_permute_b32 v97, v166, v99
	s_waitcnt lgkmcnt(4)
	v_cndmask_b32_e64 v78, v72, v76, s[10:11]
	v_cndmask_b32_e64 v79, v73, v77, s[10:11]
	v_cndmask_b32_e64 v76, v76, v72, s[10:11]
	v_cndmask_b32_e64 v77, v77, v73, s[10:11]
	v_add_u32_e32 v169, 0x10100, v168
	global_store_dwordx4 v169, v[76:79], s[12:13]
	s_waitcnt vmcnt(23)
	v_mul_f32_e32 v68, 0xbfb8aa3b, v68
	v_mul_f32_e32 v69, 0xbfb8aa3b, v69
	v_mul_f32_e32 v70, 0xbfb8aa3b, v70
	v_mul_f32_e32 v71, 0xbfb8aa3b, v71
	v_exp_f32_e32 v68, v68
	v_exp_f32_e32 v69, v69
	v_exp_f32_e32 v70, v70
	v_exp_f32_e32 v71, v71
	v_lshlrev_b32_e32 v158, 16, v206
	v_and_b32_e32 v206, 0xffff0000, v206
	v_pk_add_f32 v[68:69], v[68:69], 1.0 op_sel_hi:[1,0]
	v_pk_add_f32 v[70:71], v[70:71], 1.0 op_sel_hi:[1,0]
	v_lshlrev_b32_e32 v167, 16, v207
	v_and_b32_e32 v207, 0xffff0000, v207
	v_div_scale_f32 v140, s[6:7], v68, v68, v158
	v_div_scale_f32 v141, s[6:7], v69, v69, v206
	v_rcp_f32_e32 v144, v140
	v_rcp_f32_e32 v145, v141
	v_div_scale_f32 v142, vcc, v158, v68, v158
	v_div_scale_f32 v143, s[6:7], v206, v69, v206
	v_fma_f32 v146, -v140, v144, 1.0
	v_fma_f32 v147, -v141, v145, 1.0
	v_fmac_f32_e32 v144, v146, v144
	v_fmac_f32_e32 v145, v147, v145
	v_mul_f32_e32 v148, v142, v144
	v_mul_f32_e32 v149, v143, v145
	v_fma_f32 v146, -v140, v148, v142
	v_fma_f32 v147, -v141, v149, v143
	v_fmac_f32_e32 v148, v146, v144
	v_fmac_f32_e32 v149, v147, v145
	v_fma_f32 v146, -v140, v148, v142
	v_fma_f32 v147, -v141, v149, v143
	v_div_fmas_f32 v146, v146, v144, v148
	s_mov_b64 vcc, s[6:7]
	v_div_fixup_f32 v68, v146, v68, v158
	s_nop 1
	v_div_fmas_f32 v147, v147, v145, v149
	v_div_fixup_f32 v69, v147, v69, v206
	v_div_scale_f32 v140, s[6:7], v70, v70, v167
	v_div_scale_f32 v141, s[6:7], v71, v71, v207
	v_rcp_f32_e32 v144, v140
	v_rcp_f32_e32 v145, v141
	v_div_scale_f32 v142, vcc, v167, v70, v167
	v_div_scale_f32 v143, s[6:7], v207, v71, v207
	v_fma_f32 v146, -v140, v144, 1.0
	v_fma_f32 v147, -v141, v145, 1.0
	v_fmac_f32_e32 v144, v146, v144
	v_fmac_f32_e32 v145, v147, v145
	v_mul_f32_e32 v148, v142, v144
	v_mul_f32_e32 v149, v143, v145
	v_fma_f32 v146, -v140, v148, v142
	v_fma_f32 v147, -v141, v149, v143
	v_fmac_f32_e32 v148, v146, v144
	v_fmac_f32_e32 v149, v147, v145
	v_fma_f32 v146, -v140, v148, v142
	v_fma_f32 v147, -v141, v149, v143
	v_div_fmas_f32 v146, v146, v144, v148
	s_mov_b64 vcc, s[6:7]
	v_div_fixup_f32 v70, v146, v70, v167
	s_nop 1
	v_div_fmas_f32 v147, v147, v145, v149
	v_div_fixup_f32 v71, v147, v71, v207
	v_cvt_pk_bf16_f32 v68, v68, v69
	v_cvt_pk_bf16_f32 v69, v70, v71
	s_waitcnt vmcnt(22)
	v_mul_f32_e32 v64, 0xbfb8aa3b, v64
	v_mul_f32_e32 v65, 0xbfb8aa3b, v65
	v_mul_f32_e32 v66, 0xbfb8aa3b, v66
	v_mul_f32_e32 v67, 0xbfb8aa3b, v67
	v_exp_f32_e32 v64, v64
	v_exp_f32_e32 v65, v65
	v_exp_f32_e32 v66, v66
	v_exp_f32_e32 v67, v67
	v_lshlrev_b32_e32 v158, 16, v208
	v_and_b32_e32 v208, 0xffff0000, v208
	v_pk_add_f32 v[64:65], v[64:65], 1.0 op_sel_hi:[1,0]
	v_pk_add_f32 v[66:67], v[66:67], 1.0 op_sel_hi:[1,0]
	v_lshlrev_b32_e32 v167, 16, v209
	v_and_b32_e32 v209, 0xffff0000, v209
	v_div_scale_f32 v140, s[6:7], v64, v64, v158
	v_div_scale_f32 v141, s[6:7], v65, v65, v208
	v_rcp_f32_e32 v144, v140
	v_rcp_f32_e32 v145, v141
	v_div_scale_f32 v142, vcc, v158, v64, v158
	v_div_scale_f32 v143, s[6:7], v208, v65, v208
	v_fma_f32 v146, -v140, v144, 1.0
	v_fma_f32 v147, -v141, v145, 1.0
	v_fmac_f32_e32 v144, v146, v144
	v_fmac_f32_e32 v145, v147, v145
	v_mul_f32_e32 v148, v142, v144
	v_mul_f32_e32 v149, v143, v145
	v_fma_f32 v146, -v140, v148, v142
	v_fma_f32 v147, -v141, v149, v143
	v_fmac_f32_e32 v148, v146, v144
	v_fmac_f32_e32 v149, v147, v145
	v_fma_f32 v146, -v140, v148, v142
	v_fma_f32 v147, -v141, v149, v143
	v_div_fmas_f32 v146, v146, v144, v148
	s_mov_b64 vcc, s[6:7]
	v_div_fixup_f32 v64, v146, v64, v158
	s_nop 1
	v_div_fmas_f32 v147, v147, v145, v149
	v_div_fixup_f32 v65, v147, v65, v208
	v_div_scale_f32 v140, s[6:7], v66, v66, v167
	v_div_scale_f32 v141, s[6:7], v67, v67, v209
	v_rcp_f32_e32 v144, v140
	v_rcp_f32_e32 v145, v141
	v_div_scale_f32 v142, vcc, v167, v66, v167
	v_div_scale_f32 v143, s[6:7], v209, v67, v209
	v_fma_f32 v146, -v140, v144, 1.0
	v_fma_f32 v147, -v141, v145, 1.0
	v_fmac_f32_e32 v144, v146, v144
	v_fmac_f32_e32 v145, v147, v145
	v_mul_f32_e32 v148, v142, v144
	v_mul_f32_e32 v149, v143, v145
	v_fma_f32 v146, -v140, v148, v142
	v_fma_f32 v147, -v141, v149, v143
	v_fmac_f32_e32 v148, v146, v144
	v_fmac_f32_e32 v149, v147, v145
	v_fma_f32 v146, -v140, v148, v142
	v_fma_f32 v147, -v141, v149, v143
	v_div_fmas_f32 v146, v146, v144, v148
	s_mov_b64 vcc, s[6:7]
	v_div_fixup_f32 v66, v146, v66, v167
	s_nop 1
	v_div_fmas_f32 v147, v147, v145, v149
	v_div_fixup_f32 v67, v147, v67, v209
	v_cvt_pk_bf16_f32 v64, v64, v65
	v_cvt_pk_bf16_f32 v65, v66, v67
	v_cndmask_b32_e64 v70, v68, v64, s[8:9]
	v_cndmask_b32_e64 v71, v69, v65, s[8:9]
	v_cndmask_b32_e64 v66, v64, v68, s[8:9]
	v_cndmask_b32_e64 v67, v65, v69, s[8:9]
	ds_permute_b32 v68, v159, v70
	ds_permute_b32 v69, v159, v71
	ds_permute_b32 v64, v166, v66
	ds_permute_b32 v65, v166, v67
	s_waitcnt lgkmcnt(4)
	v_cndmask_b32_e64 v102, v96, v100, s[10:11]
	v_cndmask_b32_e64 v103, v97, v101, s[10:11]
	v_cndmask_b32_e64 v100, v100, v96, s[10:11]
	v_cndmask_b32_e64 v101, v101, v97, s[10:11]
	v_add_u32_e32 v169, 0x18000, v168
	global_store_dwordx4 v169, v[100:103], s[12:13]
	s_waitcnt vmcnt(22)
	v_mul_f32_e32 v60, 0xbfb8aa3b, v60
	v_mul_f32_e32 v61, 0xbfb8aa3b, v61
	v_mul_f32_e32 v62, 0xbfb8aa3b, v62
	v_mul_f32_e32 v63, 0xbfb8aa3b, v63
	v_exp_f32_e32 v60, v60
	v_exp_f32_e32 v61, v61
	v_exp_f32_e32 v62, v62
	v_exp_f32_e32 v63, v63
	v_lshlrev_b32_e32 v158, 16, v210
	v_and_b32_e32 v210, 0xffff0000, v210
	v_pk_add_f32 v[60:61], v[60:61], 1.0 op_sel_hi:[1,0]
	v_pk_add_f32 v[62:63], v[62:63], 1.0 op_sel_hi:[1,0]
	v_lshlrev_b32_e32 v167, 16, v211
	v_and_b32_e32 v211, 0xffff0000, v211
	v_div_scale_f32 v140, s[6:7], v60, v60, v158
	v_div_scale_f32 v141, s[6:7], v61, v61, v210
	v_rcp_f32_e32 v144, v140
	v_rcp_f32_e32 v145, v141
	v_div_scale_f32 v142, vcc, v158, v60, v158
	v_div_scale_f32 v143, s[6:7], v210, v61, v210
	v_fma_f32 v146, -v140, v144, 1.0
	v_fma_f32 v147, -v141, v145, 1.0
	v_fmac_f32_e32 v144, v146, v144
	v_fmac_f32_e32 v145, v147, v145
	v_mul_f32_e32 v148, v142, v144
	v_mul_f32_e32 v149, v143, v145
	v_fma_f32 v146, -v140, v148, v142
	v_fma_f32 v147, -v141, v149, v143
	v_fmac_f32_e32 v148, v146, v144
	v_fmac_f32_e32 v149, v147, v145
	v_fma_f32 v146, -v140, v148, v142
	v_fma_f32 v147, -v141, v149, v143
	v_div_fmas_f32 v146, v146, v144, v148
	s_mov_b64 vcc, s[6:7]
	v_div_fixup_f32 v60, v146, v60, v158
	s_nop 1
	v_div_fmas_f32 v147, v147, v145, v149
	v_div_fixup_f32 v61, v147, v61, v210
	v_div_scale_f32 v140, s[6:7], v62, v62, v167
	v_div_scale_f32 v141, s[6:7], v63, v63, v211
	v_rcp_f32_e32 v144, v140
	v_rcp_f32_e32 v145, v141
	v_div_scale_f32 v142, vcc, v167, v62, v167
	v_div_scale_f32 v143, s[6:7], v211, v63, v211
	v_fma_f32 v146, -v140, v144, 1.0
	v_fma_f32 v147, -v141, v145, 1.0
	v_fmac_f32_e32 v144, v146, v144
	v_fmac_f32_e32 v145, v147, v145
	v_mul_f32_e32 v148, v142, v144
	v_mul_f32_e32 v149, v143, v145
	v_fma_f32 v146, -v140, v148, v142
	v_fma_f32 v147, -v141, v149, v143
	v_fmac_f32_e32 v148, v146, v144
	v_fmac_f32_e32 v149, v147, v145
	v_fma_f32 v146, -v140, v148, v142
	v_fma_f32 v147, -v141, v149, v143
	v_div_fmas_f32 v146, v146, v144, v148
	s_mov_b64 vcc, s[6:7]
	v_div_fixup_f32 v62, v146, v62, v167
	s_nop 1
	v_div_fmas_f32 v147, v147, v145, v149
	v_div_fixup_f32 v63, v147, v63, v211
	v_cvt_pk_bf16_f32 v60, v60, v61
	v_cvt_pk_bf16_f32 v61, v62, v63
	s_waitcnt vmcnt(21)
	v_mul_f32_e32 v56, 0xbfb8aa3b, v56
	v_mul_f32_e32 v57, 0xbfb8aa3b, v57
	v_mul_f32_e32 v58, 0xbfb8aa3b, v58
	v_mul_f32_e32 v59, 0xbfb8aa3b, v59
	v_exp_f32_e32 v56, v56
	v_exp_f32_e32 v57, v57
	v_exp_f32_e32 v58, v58
	v_exp_f32_e32 v59, v59
	v_lshlrev_b32_e32 v158, 16, v212
	v_and_b32_e32 v212, 0xffff0000, v212
	v_pk_add_f32 v[56:57], v[56:57], 1.0 op_sel_hi:[1,0]
	v_pk_add_f32 v[58:59], v[58:59], 1.0 op_sel_hi:[1,0]
	v_lshlrev_b32_e32 v167, 16, v213
	v_and_b32_e32 v213, 0xffff0000, v213
	v_div_scale_f32 v140, s[6:7], v56, v56, v158
	v_div_scale_f32 v141, s[6:7], v57, v57, v212
	v_rcp_f32_e32 v144, v140
	v_rcp_f32_e32 v145, v141
	v_div_scale_f32 v142, vcc, v158, v56, v158
	v_div_scale_f32 v143, s[6:7], v212, v57, v212
	v_fma_f32 v146, -v140, v144, 1.0
	v_fma_f32 v147, -v141, v145, 1.0
	v_fmac_f32_e32 v144, v146, v144
	v_fmac_f32_e32 v145, v147, v145
	v_mul_f32_e32 v148, v142, v144
	v_mul_f32_e32 v149, v143, v145
	v_fma_f32 v146, -v140, v148, v142
	v_fma_f32 v147, -v141, v149, v143
	v_fmac_f32_e32 v148, v146, v144
	v_fmac_f32_e32 v149, v147, v145
	v_fma_f32 v146, -v140, v148, v142
	v_fma_f32 v147, -v141, v149, v143
	v_div_fmas_f32 v146, v146, v144, v148
	s_mov_b64 vcc, s[6:7]
	v_div_fixup_f32 v56, v146, v56, v158
	s_nop 1
	v_div_fmas_f32 v147, v147, v145, v149
	v_div_fixup_f32 v57, v147, v57, v212
	v_div_scale_f32 v140, s[6:7], v58, v58, v167
	v_div_scale_f32 v141, s[6:7], v59, v59, v213
	v_rcp_f32_e32 v144, v140
	v_rcp_f32_e32 v145, v141
	v_div_scale_f32 v142, vcc, v167, v58, v167
	v_div_scale_f32 v143, s[6:7], v213, v59, v213
	v_fma_f32 v146, -v140, v144, 1.0
	v_fma_f32 v147, -v141, v145, 1.0
	v_fmac_f32_e32 v144, v146, v144
	v_fmac_f32_e32 v145, v147, v145
	v_mul_f32_e32 v148, v142, v144
	v_mul_f32_e32 v149, v143, v145
	v_fma_f32 v146, -v140, v148, v142
	v_fma_f32 v147, -v141, v149, v143
	v_fmac_f32_e32 v148, v146, v144
	v_fmac_f32_e32 v149, v147, v145
	v_fma_f32 v146, -v140, v148, v142
	v_fma_f32 v147, -v141, v149, v143
	v_div_fmas_f32 v146, v146, v144, v148
	s_mov_b64 vcc, s[6:7]
	v_div_fixup_f32 v58, v146, v58, v167
	s_nop 1
	v_div_fmas_f32 v147, v147, v145, v149
	v_div_fixup_f32 v59, v147, v59, v213
	v_cvt_pk_bf16_f32 v56, v56, v57
	v_cvt_pk_bf16_f32 v57, v58, v59
	v_cndmask_b32_e64 v62, v60, v56, s[8:9]
	v_cndmask_b32_e64 v63, v61, v57, s[8:9]
	v_cndmask_b32_e64 v58, v56, v60, s[8:9]
	v_cndmask_b32_e64 v59, v57, v61, s[8:9]
	ds_permute_b32 v60, v159, v62
	ds_permute_b32 v61, v159, v63
	ds_permute_b32 v56, v166, v58
	ds_permute_b32 v57, v166, v59
	s_waitcnt lgkmcnt(4)
	v_cndmask_b32_e64 v70, v64, v68, s[10:11]
	v_cndmask_b32_e64 v71, v65, v69, s[10:11]
	v_cndmask_b32_e64 v68, v68, v64, s[10:11]
	v_cndmask_b32_e64 v69, v69, v65, s[10:11]
	v_add_u32_e32 v169, 0x18100, v168
	global_store_dwordx4 v169, v[68:71], s[12:13]
	s_waitcnt vmcnt(21)
	v_mul_f32_e32 v28, 0xbfb8aa3b, v28
	v_mul_f32_e32 v29, 0xbfb8aa3b, v29
	v_mul_f32_e32 v30, 0xbfb8aa3b, v30
	v_mul_f32_e32 v31, 0xbfb8aa3b, v31
	v_exp_f32_e32 v28, v28
	v_exp_f32_e32 v29, v29
	v_exp_f32_e32 v30, v30
	v_exp_f32_e32 v31, v31
	v_lshlrev_b32_e32 v158, 16, v214
	v_and_b32_e32 v214, 0xffff0000, v214
	v_pk_add_f32 v[28:29], v[28:29], 1.0 op_sel_hi:[1,0]
	v_pk_add_f32 v[30:31], v[30:31], 1.0 op_sel_hi:[1,0]
	v_lshlrev_b32_e32 v167, 16, v215
	v_and_b32_e32 v215, 0xffff0000, v215
	v_div_scale_f32 v140, s[6:7], v28, v28, v158
	v_div_scale_f32 v141, s[6:7], v29, v29, v214
	v_rcp_f32_e32 v144, v140
	v_rcp_f32_e32 v145, v141
	v_div_scale_f32 v142, vcc, v158, v28, v158
	v_div_scale_f32 v143, s[6:7], v214, v29, v214
	v_fma_f32 v146, -v140, v144, 1.0
	v_fma_f32 v147, -v141, v145, 1.0
	v_fmac_f32_e32 v144, v146, v144
	v_fmac_f32_e32 v145, v147, v145
	v_mul_f32_e32 v148, v142, v144
	v_mul_f32_e32 v149, v143, v145
	v_fma_f32 v146, -v140, v148, v142
	v_fma_f32 v147, -v141, v149, v143
	v_fmac_f32_e32 v148, v146, v144
	v_fmac_f32_e32 v149, v147, v145
	v_fma_f32 v146, -v140, v148, v142
	v_fma_f32 v147, -v141, v149, v143
	v_div_fmas_f32 v146, v146, v144, v148
	s_mov_b64 vcc, s[6:7]
	v_div_fixup_f32 v28, v146, v28, v158
	s_nop 1
	v_div_fmas_f32 v147, v147, v145, v149
	v_div_fixup_f32 v29, v147, v29, v214
	v_div_scale_f32 v140, s[6:7], v30, v30, v167
	v_div_scale_f32 v141, s[6:7], v31, v31, v215
	v_rcp_f32_e32 v144, v140
	v_rcp_f32_e32 v145, v141
	v_div_scale_f32 v142, vcc, v167, v30, v167
	v_div_scale_f32 v143, s[6:7], v215, v31, v215
	v_fma_f32 v146, -v140, v144, 1.0
	v_fma_f32 v147, -v141, v145, 1.0
	v_fmac_f32_e32 v144, v146, v144
	v_fmac_f32_e32 v145, v147, v145
	v_mul_f32_e32 v148, v142, v144
	v_mul_f32_e32 v149, v143, v145
	v_fma_f32 v146, -v140, v148, v142
	v_fma_f32 v147, -v141, v149, v143
	v_fmac_f32_e32 v148, v146, v144
	v_fmac_f32_e32 v149, v147, v145
	v_fma_f32 v146, -v140, v148, v142
	v_fma_f32 v147, -v141, v149, v143
	v_div_fmas_f32 v146, v146, v144, v148
	s_mov_b64 vcc, s[6:7]
	v_div_fixup_f32 v30, v146, v30, v167
	s_nop 1
	v_div_fmas_f32 v147, v147, v145, v149
	v_div_fixup_f32 v31, v147, v31, v215
	v_cvt_pk_bf16_f32 v28, v28, v29
	v_cvt_pk_bf16_f32 v29, v30, v31
	s_waitcnt vmcnt(20)
	v_mul_f32_e32 v24, 0xbfb8aa3b, v24
	v_mul_f32_e32 v25, 0xbfb8aa3b, v25
	v_mul_f32_e32 v26, 0xbfb8aa3b, v26
	v_mul_f32_e32 v27, 0xbfb8aa3b, v27
	v_exp_f32_e32 v24, v24
	v_exp_f32_e32 v25, v25
	v_exp_f32_e32 v26, v26
	v_exp_f32_e32 v27, v27
	v_lshlrev_b32_e32 v158, 16, v216
	v_and_b32_e32 v216, 0xffff0000, v216
	v_pk_add_f32 v[24:25], v[24:25], 1.0 op_sel_hi:[1,0]
	v_pk_add_f32 v[26:27], v[26:27], 1.0 op_sel_hi:[1,0]
	v_lshlrev_b32_e32 v167, 16, v217
	v_and_b32_e32 v217, 0xffff0000, v217
	v_div_scale_f32 v140, s[6:7], v24, v24, v158
	v_div_scale_f32 v141, s[6:7], v25, v25, v216
	v_rcp_f32_e32 v144, v140
	v_rcp_f32_e32 v145, v141
	v_div_scale_f32 v142, vcc, v158, v24, v158
	v_div_scale_f32 v143, s[6:7], v216, v25, v216
	v_fma_f32 v146, -v140, v144, 1.0
	v_fma_f32 v147, -v141, v145, 1.0
	v_fmac_f32_e32 v144, v146, v144
	v_fmac_f32_e32 v145, v147, v145
	v_mul_f32_e32 v148, v142, v144
	v_mul_f32_e32 v149, v143, v145
	v_fma_f32 v146, -v140, v148, v142
	v_fma_f32 v147, -v141, v149, v143
	v_fmac_f32_e32 v148, v146, v144
	v_fmac_f32_e32 v149, v147, v145
	v_fma_f32 v146, -v140, v148, v142
	v_fma_f32 v147, -v141, v149, v143
	v_div_fmas_f32 v146, v146, v144, v148
	s_mov_b64 vcc, s[6:7]
	v_div_fixup_f32 v24, v146, v24, v158
	s_nop 1
	v_div_fmas_f32 v147, v147, v145, v149
	v_div_fixup_f32 v25, v147, v25, v216
	v_div_scale_f32 v140, s[6:7], v26, v26, v167
	v_div_scale_f32 v141, s[6:7], v27, v27, v217
	v_rcp_f32_e32 v144, v140
	v_rcp_f32_e32 v145, v141
	v_div_scale_f32 v142, vcc, v167, v26, v167
	v_div_scale_f32 v143, s[6:7], v217, v27, v217
	v_fma_f32 v146, -v140, v144, 1.0
	v_fma_f32 v147, -v141, v145, 1.0
	v_fmac_f32_e32 v144, v146, v144
	v_fmac_f32_e32 v145, v147, v145
	v_mul_f32_e32 v148, v142, v144
	v_mul_f32_e32 v149, v143, v145
	v_fma_f32 v146, -v140, v148, v142
	v_fma_f32 v147, -v141, v149, v143
	v_fmac_f32_e32 v148, v146, v144
	v_fmac_f32_e32 v149, v147, v145
	v_fma_f32 v146, -v140, v148, v142
	v_fma_f32 v147, -v141, v149, v143
	v_div_fmas_f32 v146, v146, v144, v148
	s_mov_b64 vcc, s[6:7]
	v_div_fixup_f32 v26, v146, v26, v167
	s_nop 1
	v_div_fmas_f32 v147, v147, v145, v149
	v_div_fixup_f32 v27, v147, v27, v217
	v_cvt_pk_bf16_f32 v24, v24, v25
	v_cvt_pk_bf16_f32 v25, v26, v27
	v_cndmask_b32_e64 v30, v28, v24, s[8:9]
	v_cndmask_b32_e64 v31, v29, v25, s[8:9]
	v_cndmask_b32_e64 v26, v24, v28, s[8:9]
	v_cndmask_b32_e64 v27, v25, v29, s[8:9]
	ds_permute_b32 v28, v159, v30
	ds_permute_b32 v29, v159, v31
	ds_permute_b32 v24, v166, v26
	ds_permute_b32 v25, v166, v27
	s_waitcnt lgkmcnt(4)
	v_cndmask_b32_e64 v62, v56, v60, s[10:11]
	v_cndmask_b32_e64 v63, v57, v61, s[10:11]
	v_cndmask_b32_e64 v60, v60, v56, s[10:11]
	v_cndmask_b32_e64 v61, v61, v57, s[10:11]
	v_add_u32_e32 v169, 0x40000, v168
	global_store_dwordx4 v169, v[60:63], s[12:13]
	s_waitcnt vmcnt(20)
	v_mul_f32_e32 v52, 0xbfb8aa3b, v52
	v_mul_f32_e32 v53, 0xbfb8aa3b, v53
	v_mul_f32_e32 v54, 0xbfb8aa3b, v54
	v_mul_f32_e32 v55, 0xbfb8aa3b, v55
	v_exp_f32_e32 v52, v52
	v_exp_f32_e32 v53, v53
	v_exp_f32_e32 v54, v54
	v_exp_f32_e32 v55, v55
	v_lshlrev_b32_e32 v158, 16, v218
	v_and_b32_e32 v218, 0xffff0000, v218
	v_pk_add_f32 v[52:53], v[52:53], 1.0 op_sel_hi:[1,0]
	v_pk_add_f32 v[54:55], v[54:55], 1.0 op_sel_hi:[1,0]
	v_lshlrev_b32_e32 v167, 16, v219
	v_and_b32_e32 v219, 0xffff0000, v219
	v_div_scale_f32 v140, s[6:7], v52, v52, v158
	v_div_scale_f32 v141, s[6:7], v53, v53, v218
	v_rcp_f32_e32 v144, v140
	v_rcp_f32_e32 v145, v141
	v_div_scale_f32 v142, vcc, v158, v52, v158
	v_div_scale_f32 v143, s[6:7], v218, v53, v218
	v_fma_f32 v146, -v140, v144, 1.0
	v_fma_f32 v147, -v141, v145, 1.0
	v_fmac_f32_e32 v144, v146, v144
	v_fmac_f32_e32 v145, v147, v145
	v_mul_f32_e32 v148, v142, v144
	v_mul_f32_e32 v149, v143, v145
	v_fma_f32 v146, -v140, v148, v142
	v_fma_f32 v147, -v141, v149, v143
	v_fmac_f32_e32 v148, v146, v144
	v_fmac_f32_e32 v149, v147, v145
	v_fma_f32 v146, -v140, v148, v142
	v_fma_f32 v147, -v141, v149, v143
	v_div_fmas_f32 v146, v146, v144, v148
	s_mov_b64 vcc, s[6:7]
	v_div_fixup_f32 v52, v146, v52, v158
	s_nop 1
	v_div_fmas_f32 v147, v147, v145, v149
	v_div_fixup_f32 v53, v147, v53, v218
	v_div_scale_f32 v140, s[6:7], v54, v54, v167
	v_div_scale_f32 v141, s[6:7], v55, v55, v219
	v_rcp_f32_e32 v144, v140
	v_rcp_f32_e32 v145, v141
	v_div_scale_f32 v142, vcc, v167, v54, v167
	v_div_scale_f32 v143, s[6:7], v219, v55, v219
	v_fma_f32 v146, -v140, v144, 1.0
	v_fma_f32 v147, -v141, v145, 1.0
	v_fmac_f32_e32 v144, v146, v144
	v_fmac_f32_e32 v145, v147, v145
	v_mul_f32_e32 v148, v142, v144
	v_mul_f32_e32 v149, v143, v145
	v_fma_f32 v146, -v140, v148, v142
	v_fma_f32 v147, -v141, v149, v143
	v_fmac_f32_e32 v148, v146, v144
	v_fmac_f32_e32 v149, v147, v145
	v_fma_f32 v146, -v140, v148, v142
	v_fma_f32 v147, -v141, v149, v143
	v_div_fmas_f32 v146, v146, v144, v148
	s_mov_b64 vcc, s[6:7]
	v_div_fixup_f32 v54, v146, v54, v167
	s_nop 1
	v_div_fmas_f32 v147, v147, v145, v149
	v_div_fixup_f32 v55, v147, v55, v219
	v_cvt_pk_bf16_f32 v52, v52, v53
	v_cvt_pk_bf16_f32 v53, v54, v55
	s_waitcnt vmcnt(19)
	v_mul_f32_e32 v48, 0xbfb8aa3b, v48
	v_mul_f32_e32 v49, 0xbfb8aa3b, v49
	v_mul_f32_e32 v50, 0xbfb8aa3b, v50
	v_mul_f32_e32 v51, 0xbfb8aa3b, v51
	v_exp_f32_e32 v48, v48
	v_exp_f32_e32 v49, v49
	v_exp_f32_e32 v50, v50
	v_exp_f32_e32 v51, v51
	v_lshlrev_b32_e32 v158, 16, v220
	v_and_b32_e32 v220, 0xffff0000, v220
	v_pk_add_f32 v[48:49], v[48:49], 1.0 op_sel_hi:[1,0]
	v_pk_add_f32 v[50:51], v[50:51], 1.0 op_sel_hi:[1,0]
	v_lshlrev_b32_e32 v167, 16, v221
	v_and_b32_e32 v221, 0xffff0000, v221
	v_div_scale_f32 v140, s[6:7], v48, v48, v158
	v_div_scale_f32 v141, s[6:7], v49, v49, v220
	v_rcp_f32_e32 v144, v140
	v_rcp_f32_e32 v145, v141
	v_div_scale_f32 v142, vcc, v158, v48, v158
	v_div_scale_f32 v143, s[6:7], v220, v49, v220
	v_fma_f32 v146, -v140, v144, 1.0
	v_fma_f32 v147, -v141, v145, 1.0
	v_fmac_f32_e32 v144, v146, v144
	v_fmac_f32_e32 v145, v147, v145
	v_mul_f32_e32 v148, v142, v144
	v_mul_f32_e32 v149, v143, v145
	v_fma_f32 v146, -v140, v148, v142
	v_fma_f32 v147, -v141, v149, v143
	v_fmac_f32_e32 v148, v146, v144
	v_fmac_f32_e32 v149, v147, v145
	v_fma_f32 v146, -v140, v148, v142
	v_fma_f32 v147, -v141, v149, v143
	v_div_fmas_f32 v146, v146, v144, v148
	s_mov_b64 vcc, s[6:7]
	v_div_fixup_f32 v48, v146, v48, v158
	s_nop 1
	v_div_fmas_f32 v147, v147, v145, v149
	v_div_fixup_f32 v49, v147, v49, v220
	v_div_scale_f32 v140, s[6:7], v50, v50, v167
	v_div_scale_f32 v141, s[6:7], v51, v51, v221
	v_rcp_f32_e32 v144, v140
	v_rcp_f32_e32 v145, v141
	v_div_scale_f32 v142, vcc, v167, v50, v167
	v_div_scale_f32 v143, s[6:7], v221, v51, v221
	v_fma_f32 v146, -v140, v144, 1.0
	v_fma_f32 v147, -v141, v145, 1.0
	v_fmac_f32_e32 v144, v146, v144
	v_fmac_f32_e32 v145, v147, v145
	v_mul_f32_e32 v148, v142, v144
	v_mul_f32_e32 v149, v143, v145
	v_fma_f32 v146, -v140, v148, v142
	v_fma_f32 v147, -v141, v149, v143
	v_fmac_f32_e32 v148, v146, v144
	v_fmac_f32_e32 v149, v147, v145
	v_fma_f32 v146, -v140, v148, v142
	v_fma_f32 v147, -v141, v149, v143
	v_div_fmas_f32 v146, v146, v144, v148
	s_mov_b64 vcc, s[6:7]
	v_div_fixup_f32 v50, v146, v50, v167
	s_nop 1
	v_div_fmas_f32 v147, v147, v145, v149
	v_div_fixup_f32 v51, v147, v51, v221
	v_cvt_pk_bf16_f32 v48, v48, v49
	v_cvt_pk_bf16_f32 v49, v50, v51
	v_cndmask_b32_e64 v54, v52, v48, s[8:9]
	v_cndmask_b32_e64 v55, v53, v49, s[8:9]
	v_cndmask_b32_e64 v50, v48, v52, s[8:9]
	v_cndmask_b32_e64 v51, v49, v53, s[8:9]
	ds_permute_b32 v52, v159, v54
	ds_permute_b32 v53, v159, v55
	ds_permute_b32 v48, v166, v50
	ds_permute_b32 v49, v166, v51
	s_waitcnt lgkmcnt(4)
	v_cndmask_b32_e64 v30, v24, v28, s[10:11]
	v_cndmask_b32_e64 v31, v25, v29, s[10:11]
	v_cndmask_b32_e64 v28, v28, v24, s[10:11]
	v_cndmask_b32_e64 v29, v29, v25, s[10:11]
	v_add_u32_e32 v169, 0x40100, v168
	global_store_dwordx4 v169, v[28:31], s[12:13]
	s_waitcnt vmcnt(19)
	v_mul_f32_e32 v20, 0xbfb8aa3b, v20
	v_mul_f32_e32 v21, 0xbfb8aa3b, v21
	v_mul_f32_e32 v22, 0xbfb8aa3b, v22
	v_mul_f32_e32 v23, 0xbfb8aa3b, v23
	v_exp_f32_e32 v20, v20
	v_exp_f32_e32 v21, v21
	v_exp_f32_e32 v22, v22
	v_exp_f32_e32 v23, v23
	v_lshlrev_b32_e32 v158, 16, v222
	v_and_b32_e32 v222, 0xffff0000, v222
	v_pk_add_f32 v[20:21], v[20:21], 1.0 op_sel_hi:[1,0]
	v_pk_add_f32 v[22:23], v[22:23], 1.0 op_sel_hi:[1,0]
	v_lshlrev_b32_e32 v167, 16, v223
	v_and_b32_e32 v223, 0xffff0000, v223
	v_div_scale_f32 v140, s[6:7], v20, v20, v158
	v_div_scale_f32 v141, s[6:7], v21, v21, v222
	v_rcp_f32_e32 v144, v140
	v_rcp_f32_e32 v145, v141
	v_div_scale_f32 v142, vcc, v158, v20, v158
	v_div_scale_f32 v143, s[6:7], v222, v21, v222
	v_fma_f32 v146, -v140, v144, 1.0
	v_fma_f32 v147, -v141, v145, 1.0
	v_fmac_f32_e32 v144, v146, v144
	v_fmac_f32_e32 v145, v147, v145
	v_mul_f32_e32 v148, v142, v144
	v_mul_f32_e32 v149, v143, v145
	v_fma_f32 v146, -v140, v148, v142
	v_fma_f32 v147, -v141, v149, v143
	v_fmac_f32_e32 v148, v146, v144
	v_fmac_f32_e32 v149, v147, v145
	v_fma_f32 v146, -v140, v148, v142
	v_fma_f32 v147, -v141, v149, v143
	v_div_fmas_f32 v146, v146, v144, v148
	s_mov_b64 vcc, s[6:7]
	v_div_fixup_f32 v20, v146, v20, v158
	s_nop 1
	v_div_fmas_f32 v147, v147, v145, v149
	v_div_fixup_f32 v21, v147, v21, v222
	v_div_scale_f32 v140, s[6:7], v22, v22, v167
	v_div_scale_f32 v141, s[6:7], v23, v23, v223
	v_rcp_f32_e32 v144, v140
	v_rcp_f32_e32 v145, v141
	v_div_scale_f32 v142, vcc, v167, v22, v167
	v_div_scale_f32 v143, s[6:7], v223, v23, v223
	v_fma_f32 v146, -v140, v144, 1.0
	v_fma_f32 v147, -v141, v145, 1.0
	v_fmac_f32_e32 v144, v146, v144
	v_fmac_f32_e32 v145, v147, v145
	v_mul_f32_e32 v148, v142, v144
	v_mul_f32_e32 v149, v143, v145
	v_fma_f32 v146, -v140, v148, v142
	v_fma_f32 v147, -v141, v149, v143
	v_fmac_f32_e32 v148, v146, v144
	v_fmac_f32_e32 v149, v147, v145
	v_fma_f32 v146, -v140, v148, v142
	v_fma_f32 v147, -v141, v149, v143
	v_div_fmas_f32 v146, v146, v144, v148
	s_mov_b64 vcc, s[6:7]
	v_div_fixup_f32 v22, v146, v22, v167
	s_nop 1
	v_div_fmas_f32 v147, v147, v145, v149
	v_div_fixup_f32 v23, v147, v23, v223
	v_cvt_pk_bf16_f32 v20, v20, v21
	v_cvt_pk_bf16_f32 v21, v22, v23
	s_waitcnt vmcnt(18)
	v_mul_f32_e32 v16, 0xbfb8aa3b, v16
	v_mul_f32_e32 v17, 0xbfb8aa3b, v17
	v_mul_f32_e32 v18, 0xbfb8aa3b, v18
	v_mul_f32_e32 v19, 0xbfb8aa3b, v19
	v_exp_f32_e32 v16, v16
	v_exp_f32_e32 v17, v17
	v_exp_f32_e32 v18, v18
	v_exp_f32_e32 v19, v19
	v_lshlrev_b32_e32 v158, 16, v224
	v_and_b32_e32 v224, 0xffff0000, v224
	v_pk_add_f32 v[16:17], v[16:17], 1.0 op_sel_hi:[1,0]
	v_pk_add_f32 v[18:19], v[18:19], 1.0 op_sel_hi:[1,0]
	v_lshlrev_b32_e32 v167, 16, v225
	v_and_b32_e32 v225, 0xffff0000, v225
	v_div_scale_f32 v140, s[6:7], v16, v16, v158
	v_div_scale_f32 v141, s[6:7], v17, v17, v224
	v_rcp_f32_e32 v144, v140
	v_rcp_f32_e32 v145, v141
	v_div_scale_f32 v142, vcc, v158, v16, v158
	v_div_scale_f32 v143, s[6:7], v224, v17, v224
	v_fma_f32 v146, -v140, v144, 1.0
	v_fma_f32 v147, -v141, v145, 1.0
	v_fmac_f32_e32 v144, v146, v144
	v_fmac_f32_e32 v145, v147, v145
	v_mul_f32_e32 v148, v142, v144
	v_mul_f32_e32 v149, v143, v145
	v_fma_f32 v146, -v140, v148, v142
	v_fma_f32 v147, -v141, v149, v143
	v_fmac_f32_e32 v148, v146, v144
	v_fmac_f32_e32 v149, v147, v145
	v_fma_f32 v146, -v140, v148, v142
	v_fma_f32 v147, -v141, v149, v143
	v_div_fmas_f32 v146, v146, v144, v148
	s_mov_b64 vcc, s[6:7]
	v_div_fixup_f32 v16, v146, v16, v158
	s_nop 1
	v_div_fmas_f32 v147, v147, v145, v149
	v_div_fixup_f32 v17, v147, v17, v224
	v_div_scale_f32 v140, s[6:7], v18, v18, v167
	v_div_scale_f32 v141, s[6:7], v19, v19, v225
	v_rcp_f32_e32 v144, v140
	v_rcp_f32_e32 v145, v141
	v_div_scale_f32 v142, vcc, v167, v18, v167
	v_div_scale_f32 v143, s[6:7], v225, v19, v225
	v_fma_f32 v146, -v140, v144, 1.0
	v_fma_f32 v147, -v141, v145, 1.0
	v_fmac_f32_e32 v144, v146, v144
	v_fmac_f32_e32 v145, v147, v145
	v_mul_f32_e32 v148, v142, v144
	v_mul_f32_e32 v149, v143, v145
	v_fma_f32 v146, -v140, v148, v142
	v_fma_f32 v147, -v141, v149, v143
	v_fmac_f32_e32 v148, v146, v144
	v_fmac_f32_e32 v149, v147, v145
	v_fma_f32 v146, -v140, v148, v142
	v_fma_f32 v147, -v141, v149, v143
	v_div_fmas_f32 v146, v146, v144, v148
	s_mov_b64 vcc, s[6:7]
	v_div_fixup_f32 v18, v146, v18, v167
	s_nop 1
	v_div_fmas_f32 v147, v147, v145, v149
	v_div_fixup_f32 v19, v147, v19, v225
	v_cvt_pk_bf16_f32 v16, v16, v17
	v_cvt_pk_bf16_f32 v17, v18, v19
	v_cndmask_b32_e64 v22, v20, v16, s[8:9]
	v_cndmask_b32_e64 v23, v21, v17, s[8:9]
	v_cndmask_b32_e64 v18, v16, v20, s[8:9]
	v_cndmask_b32_e64 v19, v17, v21, s[8:9]
	ds_permute_b32 v20, v159, v22
	ds_permute_b32 v21, v159, v23
	ds_permute_b32 v16, v166, v18
	ds_permute_b32 v17, v166, v19
	s_waitcnt lgkmcnt(4)
	v_cndmask_b32_e64 v54, v48, v52, s[10:11]
	v_cndmask_b32_e64 v55, v49, v53, s[10:11]
	v_cndmask_b32_e64 v52, v52, v48, s[10:11]
	v_cndmask_b32_e64 v53, v53, v49, s[10:11]
	v_add_u32_e32 v169, 0x48000, v168
	global_store_dwordx4 v169, v[52:55], s[12:13]
	s_waitcnt vmcnt(18)
	v_mul_f32_e32 v44, 0xbfb8aa3b, v44
	v_mul_f32_e32 v45, 0xbfb8aa3b, v45
	v_mul_f32_e32 v46, 0xbfb8aa3b, v46
	v_mul_f32_e32 v47, 0xbfb8aa3b, v47
	v_exp_f32_e32 v44, v44
	v_exp_f32_e32 v45, v45
	v_exp_f32_e32 v46, v46
	v_exp_f32_e32 v47, v47
	v_lshlrev_b32_e32 v158, 16, v226
	v_and_b32_e32 v226, 0xffff0000, v226
	v_pk_add_f32 v[44:45], v[44:45], 1.0 op_sel_hi:[1,0]
	v_pk_add_f32 v[46:47], v[46:47], 1.0 op_sel_hi:[1,0]
	v_lshlrev_b32_e32 v167, 16, v227
	v_and_b32_e32 v227, 0xffff0000, v227
	v_div_scale_f32 v140, s[6:7], v44, v44, v158
	v_div_scale_f32 v141, s[6:7], v45, v45, v226
	v_rcp_f32_e32 v144, v140
	v_rcp_f32_e32 v145, v141
	v_div_scale_f32 v142, vcc, v158, v44, v158
	v_div_scale_f32 v143, s[6:7], v226, v45, v226
	v_fma_f32 v146, -v140, v144, 1.0
	v_fma_f32 v147, -v141, v145, 1.0
	v_fmac_f32_e32 v144, v146, v144
	v_fmac_f32_e32 v145, v147, v145
	v_mul_f32_e32 v148, v142, v144
	v_mul_f32_e32 v149, v143, v145
	v_fma_f32 v146, -v140, v148, v142
	v_fma_f32 v147, -v141, v149, v143
	v_fmac_f32_e32 v148, v146, v144
	v_fmac_f32_e32 v149, v147, v145
	v_fma_f32 v146, -v140, v148, v142
	v_fma_f32 v147, -v141, v149, v143
	v_div_fmas_f32 v146, v146, v144, v148
	s_mov_b64 vcc, s[6:7]
	v_div_fixup_f32 v44, v146, v44, v158
	s_nop 1
	v_div_fmas_f32 v147, v147, v145, v149
	v_div_fixup_f32 v45, v147, v45, v226
	v_div_scale_f32 v140, s[6:7], v46, v46, v167
	v_div_scale_f32 v141, s[6:7], v47, v47, v227
	v_rcp_f32_e32 v144, v140
	v_rcp_f32_e32 v145, v141
	v_div_scale_f32 v142, vcc, v167, v46, v167
	v_div_scale_f32 v143, s[6:7], v227, v47, v227
	v_fma_f32 v146, -v140, v144, 1.0
	v_fma_f32 v147, -v141, v145, 1.0
	v_fmac_f32_e32 v144, v146, v144
	v_fmac_f32_e32 v145, v147, v145
	v_mul_f32_e32 v148, v142, v144
	v_mul_f32_e32 v149, v143, v145
	v_fma_f32 v146, -v140, v148, v142
	v_fma_f32 v147, -v141, v149, v143
	v_fmac_f32_e32 v148, v146, v144
	v_fmac_f32_e32 v149, v147, v145
	v_fma_f32 v146, -v140, v148, v142
	v_fma_f32 v147, -v141, v149, v143
	v_div_fmas_f32 v146, v146, v144, v148
	s_mov_b64 vcc, s[6:7]
	v_div_fixup_f32 v46, v146, v46, v167
	s_nop 1
	v_div_fmas_f32 v147, v147, v145, v149
	v_div_fixup_f32 v47, v147, v47, v227
	v_cvt_pk_bf16_f32 v44, v44, v45
	v_cvt_pk_bf16_f32 v45, v46, v47
	s_waitcnt vmcnt(17)
	v_mul_f32_e32 v40, 0xbfb8aa3b, v40
	v_mul_f32_e32 v41, 0xbfb8aa3b, v41
	v_mul_f32_e32 v42, 0xbfb8aa3b, v42
	v_mul_f32_e32 v43, 0xbfb8aa3b, v43
	v_exp_f32_e32 v40, v40
	v_exp_f32_e32 v41, v41
	v_exp_f32_e32 v42, v42
	v_exp_f32_e32 v43, v43
	v_lshlrev_b32_e32 v158, 16, v228
	v_and_b32_e32 v228, 0xffff0000, v228
	v_pk_add_f32 v[40:41], v[40:41], 1.0 op_sel_hi:[1,0]
	v_pk_add_f32 v[42:43], v[42:43], 1.0 op_sel_hi:[1,0]
	v_lshlrev_b32_e32 v167, 16, v229
	v_and_b32_e32 v229, 0xffff0000, v229
	v_div_scale_f32 v140, s[6:7], v40, v40, v158
	v_div_scale_f32 v141, s[6:7], v41, v41, v228
	v_rcp_f32_e32 v144, v140
	v_rcp_f32_e32 v145, v141
	v_div_scale_f32 v142, vcc, v158, v40, v158
	v_div_scale_f32 v143, s[6:7], v228, v41, v228
	v_fma_f32 v146, -v140, v144, 1.0
	v_fma_f32 v147, -v141, v145, 1.0
	v_fmac_f32_e32 v144, v146, v144
	v_fmac_f32_e32 v145, v147, v145
	v_mul_f32_e32 v148, v142, v144
	v_mul_f32_e32 v149, v143, v145
	v_fma_f32 v146, -v140, v148, v142
	v_fma_f32 v147, -v141, v149, v143
	v_fmac_f32_e32 v148, v146, v144
	v_fmac_f32_e32 v149, v147, v145
	v_fma_f32 v146, -v140, v148, v142
	v_fma_f32 v147, -v141, v149, v143
	v_div_fmas_f32 v146, v146, v144, v148
	s_mov_b64 vcc, s[6:7]
	v_div_fixup_f32 v40, v146, v40, v158
	s_nop 1
	v_div_fmas_f32 v147, v147, v145, v149
	v_div_fixup_f32 v41, v147, v41, v228
	v_div_scale_f32 v140, s[6:7], v42, v42, v167
	v_div_scale_f32 v141, s[6:7], v43, v43, v229
	v_rcp_f32_e32 v144, v140
	v_rcp_f32_e32 v145, v141
	v_div_scale_f32 v142, vcc, v167, v42, v167
	v_div_scale_f32 v143, s[6:7], v229, v43, v229
	v_fma_f32 v146, -v140, v144, 1.0
	v_fma_f32 v147, -v141, v145, 1.0
	v_fmac_f32_e32 v144, v146, v144
	v_fmac_f32_e32 v145, v147, v145
	v_mul_f32_e32 v148, v142, v144
	v_mul_f32_e32 v149, v143, v145
	v_fma_f32 v146, -v140, v148, v142
	v_fma_f32 v147, -v141, v149, v143
	v_fmac_f32_e32 v148, v146, v144
	v_fmac_f32_e32 v149, v147, v145
	v_fma_f32 v146, -v140, v148, v142
	v_fma_f32 v147, -v141, v149, v143
	v_div_fmas_f32 v146, v146, v144, v148
	s_mov_b64 vcc, s[6:7]
	v_div_fixup_f32 v42, v146, v42, v167
	s_nop 1
	v_div_fmas_f32 v147, v147, v145, v149
	v_div_fixup_f32 v43, v147, v43, v229
	v_cvt_pk_bf16_f32 v40, v40, v41
	v_cvt_pk_bf16_f32 v41, v42, v43
	v_cndmask_b32_e64 v46, v44, v40, s[8:9]
	v_cndmask_b32_e64 v47, v45, v41, s[8:9]
	v_cndmask_b32_e64 v42, v40, v44, s[8:9]
	v_cndmask_b32_e64 v43, v41, v45, s[8:9]
	ds_permute_b32 v44, v159, v46
	ds_permute_b32 v45, v159, v47
	ds_permute_b32 v40, v166, v42
	ds_permute_b32 v41, v166, v43
	s_waitcnt lgkmcnt(4)
	v_cndmask_b32_e64 v22, v16, v20, s[10:11]
	v_cndmask_b32_e64 v23, v17, v21, s[10:11]
	v_cndmask_b32_e64 v20, v20, v16, s[10:11]
	v_cndmask_b32_e64 v21, v21, v17, s[10:11]
	v_add_u32_e32 v169, 0x48100, v168
	global_store_dwordx4 v169, v[20:23], s[12:13]
	s_waitcnt vmcnt(17)
	v_mul_f32_e32 v12, 0xbfb8aa3b, v12
	v_mul_f32_e32 v13, 0xbfb8aa3b, v13
	v_mul_f32_e32 v14, 0xbfb8aa3b, v14
	v_mul_f32_e32 v15, 0xbfb8aa3b, v15
	v_exp_f32_e32 v12, v12
	v_exp_f32_e32 v13, v13
	v_exp_f32_e32 v14, v14
	v_exp_f32_e32 v15, v15
	v_lshlrev_b32_e32 v158, 16, v230
	v_and_b32_e32 v230, 0xffff0000, v230
	v_pk_add_f32 v[12:13], v[12:13], 1.0 op_sel_hi:[1,0]
	v_pk_add_f32 v[14:15], v[14:15], 1.0 op_sel_hi:[1,0]
	v_lshlrev_b32_e32 v167, 16, v231
	v_and_b32_e32 v231, 0xffff0000, v231
	v_div_scale_f32 v140, s[6:7], v12, v12, v158
	v_div_scale_f32 v141, s[6:7], v13, v13, v230
	v_rcp_f32_e32 v144, v140
	v_rcp_f32_e32 v145, v141
	v_div_scale_f32 v142, vcc, v158, v12, v158
	v_div_scale_f32 v143, s[6:7], v230, v13, v230
	v_fma_f32 v146, -v140, v144, 1.0
	v_fma_f32 v147, -v141, v145, 1.0
	v_fmac_f32_e32 v144, v146, v144
	v_fmac_f32_e32 v145, v147, v145
	v_mul_f32_e32 v148, v142, v144
	v_mul_f32_e32 v149, v143, v145
	v_fma_f32 v146, -v140, v148, v142
	v_fma_f32 v147, -v141, v149, v143
	v_fmac_f32_e32 v148, v146, v144
	v_fmac_f32_e32 v149, v147, v145
	v_fma_f32 v146, -v140, v148, v142
	v_fma_f32 v147, -v141, v149, v143
	v_div_fmas_f32 v146, v146, v144, v148
	s_mov_b64 vcc, s[6:7]
	v_div_fixup_f32 v12, v146, v12, v158
	s_nop 1
	v_div_fmas_f32 v147, v147, v145, v149
	v_div_fixup_f32 v13, v147, v13, v230
	v_div_scale_f32 v140, s[6:7], v14, v14, v167
	v_div_scale_f32 v141, s[6:7], v15, v15, v231
	v_rcp_f32_e32 v144, v140
	v_rcp_f32_e32 v145, v141
	v_div_scale_f32 v142, vcc, v167, v14, v167
	v_div_scale_f32 v143, s[6:7], v231, v15, v231
	v_fma_f32 v146, -v140, v144, 1.0
	v_fma_f32 v147, -v141, v145, 1.0
	v_fmac_f32_e32 v144, v146, v144
	v_fmac_f32_e32 v145, v147, v145
	v_mul_f32_e32 v148, v142, v144
	v_mul_f32_e32 v149, v143, v145
	v_fma_f32 v146, -v140, v148, v142
	v_fma_f32 v147, -v141, v149, v143
	v_fmac_f32_e32 v148, v146, v144
	v_fmac_f32_e32 v149, v147, v145
	v_fma_f32 v146, -v140, v148, v142
	v_fma_f32 v147, -v141, v149, v143
	v_div_fmas_f32 v146, v146, v144, v148
	s_mov_b64 vcc, s[6:7]
	v_div_fixup_f32 v14, v146, v14, v167
	s_nop 1
	v_div_fmas_f32 v147, v147, v145, v149
	v_div_fixup_f32 v15, v147, v15, v231
	v_cvt_pk_bf16_f32 v12, v12, v13
	v_cvt_pk_bf16_f32 v13, v14, v15
	s_waitcnt vmcnt(16)
	v_mul_f32_e32 v8, 0xbfb8aa3b, v8
	v_mul_f32_e32 v9, 0xbfb8aa3b, v9
	v_mul_f32_e32 v10, 0xbfb8aa3b, v10
	v_mul_f32_e32 v11, 0xbfb8aa3b, v11
	v_exp_f32_e32 v8, v8
	v_exp_f32_e32 v9, v9
	v_exp_f32_e32 v10, v10
	v_exp_f32_e32 v11, v11
	v_lshlrev_b32_e32 v158, 16, v232
	v_and_b32_e32 v232, 0xffff0000, v232
	v_pk_add_f32 v[8:9], v[8:9], 1.0 op_sel_hi:[1,0]
	v_pk_add_f32 v[10:11], v[10:11], 1.0 op_sel_hi:[1,0]
	v_lshlrev_b32_e32 v167, 16, v233
	v_and_b32_e32 v233, 0xffff0000, v233
	v_div_scale_f32 v140, s[6:7], v8, v8, v158
	v_div_scale_f32 v141, s[6:7], v9, v9, v232
	v_rcp_f32_e32 v144, v140
	v_rcp_f32_e32 v145, v141
	v_div_scale_f32 v142, vcc, v158, v8, v158
	v_div_scale_f32 v143, s[6:7], v232, v9, v232
	v_fma_f32 v146, -v140, v144, 1.0
	v_fma_f32 v147, -v141, v145, 1.0
	v_fmac_f32_e32 v144, v146, v144
	v_fmac_f32_e32 v145, v147, v145
	v_mul_f32_e32 v148, v142, v144
	v_mul_f32_e32 v149, v143, v145
	v_fma_f32 v146, -v140, v148, v142
	v_fma_f32 v147, -v141, v149, v143
	v_fmac_f32_e32 v148, v146, v144
	v_fmac_f32_e32 v149, v147, v145
	v_fma_f32 v146, -v140, v148, v142
	v_fma_f32 v147, -v141, v149, v143
	v_div_fmas_f32 v146, v146, v144, v148
	s_mov_b64 vcc, s[6:7]
	v_div_fixup_f32 v8, v146, v8, v158
	s_nop 1
	v_div_fmas_f32 v147, v147, v145, v149
	v_div_fixup_f32 v9, v147, v9, v232
	v_div_scale_f32 v140, s[6:7], v10, v10, v167
	v_div_scale_f32 v141, s[6:7], v11, v11, v233
	v_rcp_f32_e32 v144, v140
	v_rcp_f32_e32 v145, v141
	v_div_scale_f32 v142, vcc, v167, v10, v167
	v_div_scale_f32 v143, s[6:7], v233, v11, v233
	v_fma_f32 v146, -v140, v144, 1.0
	v_fma_f32 v147, -v141, v145, 1.0
	v_fmac_f32_e32 v144, v146, v144
	v_fmac_f32_e32 v145, v147, v145
	v_mul_f32_e32 v148, v142, v144
	v_mul_f32_e32 v149, v143, v145
	v_fma_f32 v146, -v140, v148, v142
	v_fma_f32 v147, -v141, v149, v143
	v_fmac_f32_e32 v148, v146, v144
	v_fmac_f32_e32 v149, v147, v145
	v_fma_f32 v146, -v140, v148, v142
	v_fma_f32 v147, -v141, v149, v143
	v_div_fmas_f32 v146, v146, v144, v148
	s_mov_b64 vcc, s[6:7]
	v_div_fixup_f32 v10, v146, v10, v167
	s_nop 1
	v_div_fmas_f32 v147, v147, v145, v149
	v_div_fixup_f32 v11, v147, v11, v233
	v_cvt_pk_bf16_f32 v8, v8, v9
	v_cvt_pk_bf16_f32 v9, v10, v11
	v_cndmask_b32_e64 v14, v12, v8, s[8:9]
	v_cndmask_b32_e64 v15, v13, v9, s[8:9]
	v_cndmask_b32_e64 v10, v8, v12, s[8:9]
	v_cndmask_b32_e64 v11, v9, v13, s[8:9]
	ds_permute_b32 v12, v159, v14
	ds_permute_b32 v13, v159, v15
	ds_permute_b32 v8, v166, v10
	ds_permute_b32 v9, v166, v11
	s_waitcnt lgkmcnt(4)
	v_cndmask_b32_e64 v46, v40, v44, s[10:11]
	v_cndmask_b32_e64 v47, v41, v45, s[10:11]
	v_cndmask_b32_e64 v44, v44, v40, s[10:11]
	v_cndmask_b32_e64 v45, v45, v41, s[10:11]
	v_add_u32_e32 v169, 0x50000, v168
	global_store_dwordx4 v169, v[44:47], s[12:13]
	s_waitcnt vmcnt(16)
	v_mul_f32_e32 v36, 0xbfb8aa3b, v36
	v_mul_f32_e32 v37, 0xbfb8aa3b, v37
	v_mul_f32_e32 v38, 0xbfb8aa3b, v38
	v_mul_f32_e32 v39, 0xbfb8aa3b, v39
	v_exp_f32_e32 v36, v36
	v_exp_f32_e32 v37, v37
	v_exp_f32_e32 v38, v38
	v_exp_f32_e32 v39, v39
	v_lshlrev_b32_e32 v158, 16, v150
	v_and_b32_e32 v150, 0xffff0000, v150
	v_pk_add_f32 v[36:37], v[36:37], 1.0 op_sel_hi:[1,0]
	v_pk_add_f32 v[38:39], v[38:39], 1.0 op_sel_hi:[1,0]
	v_lshlrev_b32_e32 v167, 16, v151
	v_and_b32_e32 v151, 0xffff0000, v151
	v_div_scale_f32 v140, s[6:7], v36, v36, v158
	v_div_scale_f32 v141, s[6:7], v37, v37, v150
	v_rcp_f32_e32 v144, v140
	v_rcp_f32_e32 v145, v141
	v_div_scale_f32 v142, vcc, v158, v36, v158
	v_div_scale_f32 v143, s[6:7], v150, v37, v150
	v_fma_f32 v146, -v140, v144, 1.0
	v_fma_f32 v147, -v141, v145, 1.0
	v_fmac_f32_e32 v144, v146, v144
	v_fmac_f32_e32 v145, v147, v145
	v_mul_f32_e32 v148, v142, v144
	v_mul_f32_e32 v149, v143, v145
	v_fma_f32 v146, -v140, v148, v142
	v_fma_f32 v147, -v141, v149, v143
	v_fmac_f32_e32 v148, v146, v144
	v_fmac_f32_e32 v149, v147, v145
	v_fma_f32 v146, -v140, v148, v142
	v_fma_f32 v147, -v141, v149, v143
	v_div_fmas_f32 v146, v146, v144, v148
	s_mov_b64 vcc, s[6:7]
	v_div_fixup_f32 v36, v146, v36, v158
	s_nop 1
	v_div_fmas_f32 v147, v147, v145, v149
	v_div_fixup_f32 v37, v147, v37, v150
	v_div_scale_f32 v140, s[6:7], v38, v38, v167
	v_div_scale_f32 v141, s[6:7], v39, v39, v151
	v_rcp_f32_e32 v144, v140
	v_rcp_f32_e32 v145, v141
	v_div_scale_f32 v142, vcc, v167, v38, v167
	v_div_scale_f32 v143, s[6:7], v151, v39, v151
	v_fma_f32 v146, -v140, v144, 1.0
	v_fma_f32 v147, -v141, v145, 1.0
	v_fmac_f32_e32 v144, v146, v144
	v_fmac_f32_e32 v145, v147, v145
	v_mul_f32_e32 v148, v142, v144
	v_mul_f32_e32 v149, v143, v145
	v_fma_f32 v146, -v140, v148, v142
	v_fma_f32 v147, -v141, v149, v143
	v_fmac_f32_e32 v148, v146, v144
	v_fmac_f32_e32 v149, v147, v145
	v_fma_f32 v146, -v140, v148, v142
	v_fma_f32 v147, -v141, v149, v143
	v_div_fmas_f32 v146, v146, v144, v148
	s_mov_b64 vcc, s[6:7]
	v_div_fixup_f32 v38, v146, v38, v167
	s_nop 1
	v_div_fmas_f32 v147, v147, v145, v149
	v_div_fixup_f32 v39, v147, v39, v151
	v_cvt_pk_bf16_f32 v36, v36, v37
	v_cvt_pk_bf16_f32 v37, v38, v39
	s_waitcnt vmcnt(15)
	v_mul_f32_e32 v32, 0xbfb8aa3b, v32
	v_mul_f32_e32 v33, 0xbfb8aa3b, v33
	v_mul_f32_e32 v34, 0xbfb8aa3b, v34
	v_mul_f32_e32 v35, 0xbfb8aa3b, v35
	v_exp_f32_e32 v32, v32
	v_exp_f32_e32 v33, v33
	v_exp_f32_e32 v34, v34
	v_exp_f32_e32 v35, v35
	v_lshlrev_b32_e32 v158, 16, v152
	v_and_b32_e32 v152, 0xffff0000, v152
	v_pk_add_f32 v[32:33], v[32:33], 1.0 op_sel_hi:[1,0]
	v_pk_add_f32 v[34:35], v[34:35], 1.0 op_sel_hi:[1,0]
	v_lshlrev_b32_e32 v167, 16, v153
	v_and_b32_e32 v153, 0xffff0000, v153
	v_div_scale_f32 v140, s[6:7], v32, v32, v158
	v_div_scale_f32 v141, s[6:7], v33, v33, v152
	v_rcp_f32_e32 v144, v140
	v_rcp_f32_e32 v145, v141
	v_div_scale_f32 v142, vcc, v158, v32, v158
	v_div_scale_f32 v143, s[6:7], v152, v33, v152
	v_fma_f32 v146, -v140, v144, 1.0
	v_fma_f32 v147, -v141, v145, 1.0
	v_fmac_f32_e32 v144, v146, v144
	v_fmac_f32_e32 v145, v147, v145
	v_mul_f32_e32 v148, v142, v144
	v_mul_f32_e32 v149, v143, v145
	v_fma_f32 v146, -v140, v148, v142
	v_fma_f32 v147, -v141, v149, v143
	v_fmac_f32_e32 v148, v146, v144
	v_fmac_f32_e32 v149, v147, v145
	v_fma_f32 v146, -v140, v148, v142
	v_fma_f32 v147, -v141, v149, v143
	v_div_fmas_f32 v146, v146, v144, v148
	s_mov_b64 vcc, s[6:7]
	v_div_fixup_f32 v32, v146, v32, v158
	s_nop 1
	v_div_fmas_f32 v147, v147, v145, v149
	v_div_fixup_f32 v33, v147, v33, v152
	v_div_scale_f32 v140, s[6:7], v34, v34, v167
	v_div_scale_f32 v141, s[6:7], v35, v35, v153
	v_rcp_f32_e32 v144, v140
	v_rcp_f32_e32 v145, v141
	v_div_scale_f32 v142, vcc, v167, v34, v167
	v_div_scale_f32 v143, s[6:7], v153, v35, v153
	v_fma_f32 v146, -v140, v144, 1.0
	v_fma_f32 v147, -v141, v145, 1.0
	v_fmac_f32_e32 v144, v146, v144
	v_fmac_f32_e32 v145, v147, v145
	v_mul_f32_e32 v148, v142, v144
	v_mul_f32_e32 v149, v143, v145
	v_fma_f32 v146, -v140, v148, v142
	v_fma_f32 v147, -v141, v149, v143
	v_fmac_f32_e32 v148, v146, v144
	v_fmac_f32_e32 v149, v147, v145
	v_fma_f32 v146, -v140, v148, v142
	v_fma_f32 v147, -v141, v149, v143
	v_div_fmas_f32 v146, v146, v144, v148
	s_mov_b64 vcc, s[6:7]
	v_div_fixup_f32 v34, v146, v34, v167
	s_nop 1
	v_div_fmas_f32 v147, v147, v145, v149
	v_div_fixup_f32 v35, v147, v35, v153
	v_cvt_pk_bf16_f32 v32, v32, v33
	v_cvt_pk_bf16_f32 v33, v34, v35
	v_cndmask_b32_e64 v38, v36, v32, s[8:9]
	v_cndmask_b32_e64 v39, v37, v33, s[8:9]
	v_cndmask_b32_e64 v34, v32, v36, s[8:9]
	v_cndmask_b32_e64 v35, v33, v37, s[8:9]
	ds_permute_b32 v36, v159, v38
	ds_permute_b32 v37, v159, v39
	ds_permute_b32 v32, v166, v34
	ds_permute_b32 v33, v166, v35
	s_waitcnt lgkmcnt(4)
	v_cndmask_b32_e64 v14, v8, v12, s[10:11]
	v_cndmask_b32_e64 v15, v9, v13, s[10:11]
	v_cndmask_b32_e64 v12, v12, v8, s[10:11]
	v_cndmask_b32_e64 v13, v13, v9, s[10:11]
	v_add_u32_e32 v169, 0x50100, v168
	global_store_dwordx4 v169, v[12:15], s[12:13]
	s_waitcnt vmcnt(15)
	v_mul_f32_e32 v4, 0xbfb8aa3b, v4
	v_mul_f32_e32 v5, 0xbfb8aa3b, v5
	v_mul_f32_e32 v6, 0xbfb8aa3b, v6
	v_mul_f32_e32 v7, 0xbfb8aa3b, v7
	v_exp_f32_e32 v4, v4
	v_exp_f32_e32 v5, v5
	v_exp_f32_e32 v6, v6
	v_exp_f32_e32 v7, v7
	v_lshlrev_b32_e32 v158, 16, v154
	v_and_b32_e32 v154, 0xffff0000, v154
	v_pk_add_f32 v[4:5], v[4:5], 1.0 op_sel_hi:[1,0]
	v_pk_add_f32 v[6:7], v[6:7], 1.0 op_sel_hi:[1,0]
	v_lshlrev_b32_e32 v167, 16, v155
	v_and_b32_e32 v155, 0xffff0000, v155
	v_div_scale_f32 v140, s[6:7], v4, v4, v158
	v_div_scale_f32 v141, s[6:7], v5, v5, v154
	v_rcp_f32_e32 v144, v140
	v_rcp_f32_e32 v145, v141
	v_div_scale_f32 v142, vcc, v158, v4, v158
	v_div_scale_f32 v143, s[6:7], v154, v5, v154
	v_fma_f32 v146, -v140, v144, 1.0
	v_fma_f32 v147, -v141, v145, 1.0
	v_fmac_f32_e32 v144, v146, v144
	v_fmac_f32_e32 v145, v147, v145
	v_mul_f32_e32 v148, v142, v144
	v_mul_f32_e32 v149, v143, v145
	v_fma_f32 v146, -v140, v148, v142
	v_fma_f32 v147, -v141, v149, v143
	v_fmac_f32_e32 v148, v146, v144
	v_fmac_f32_e32 v149, v147, v145
	v_fma_f32 v146, -v140, v148, v142
	v_fma_f32 v147, -v141, v149, v143
	v_div_fmas_f32 v146, v146, v144, v148
	s_mov_b64 vcc, s[6:7]
	v_div_fixup_f32 v4, v146, v4, v158
	s_nop 1
	v_div_fmas_f32 v147, v147, v145, v149
	v_div_fixup_f32 v5, v147, v5, v154
	v_div_scale_f32 v140, s[6:7], v6, v6, v167
	v_div_scale_f32 v141, s[6:7], v7, v7, v155
	v_rcp_f32_e32 v144, v140
	v_rcp_f32_e32 v145, v141
	v_div_scale_f32 v142, vcc, v167, v6, v167
	v_div_scale_f32 v143, s[6:7], v155, v7, v155
	v_fma_f32 v146, -v140, v144, 1.0
	v_fma_f32 v147, -v141, v145, 1.0
	v_fmac_f32_e32 v144, v146, v144
	v_fmac_f32_e32 v145, v147, v145
	v_mul_f32_e32 v148, v142, v144
	v_mul_f32_e32 v149, v143, v145
	v_fma_f32 v146, -v140, v148, v142
	v_fma_f32 v147, -v141, v149, v143
	v_fmac_f32_e32 v148, v146, v144
	v_fmac_f32_e32 v149, v147, v145
	v_fma_f32 v146, -v140, v148, v142
	v_fma_f32 v147, -v141, v149, v143
	v_div_fmas_f32 v146, v146, v144, v148
	s_mov_b64 vcc, s[6:7]
	v_div_fixup_f32 v6, v146, v6, v167
	s_nop 1
	v_div_fmas_f32 v147, v147, v145, v149
	v_div_fixup_f32 v7, v147, v7, v155
	v_cvt_pk_bf16_f32 v4, v4, v5
	v_cvt_pk_bf16_f32 v5, v6, v7
	s_waitcnt vmcnt(14)
	v_mul_f32_e32 v0, 0xbfb8aa3b, v0
	v_mul_f32_e32 v1, 0xbfb8aa3b, v1
	v_mul_f32_e32 v2, 0xbfb8aa3b, v2
	v_mul_f32_e32 v3, 0xbfb8aa3b, v3
	v_exp_f32_e32 v0, v0
	v_exp_f32_e32 v1, v1
	v_exp_f32_e32 v2, v2
	v_exp_f32_e32 v3, v3
	v_lshlrev_b32_e32 v158, 16, v156
	v_and_b32_e32 v156, 0xffff0000, v156
	v_pk_add_f32 v[0:1], v[0:1], 1.0 op_sel_hi:[1,0]
	v_pk_add_f32 v[2:3], v[2:3], 1.0 op_sel_hi:[1,0]
	v_lshlrev_b32_e32 v167, 16, v157
	v_and_b32_e32 v157, 0xffff0000, v157
	v_div_scale_f32 v140, s[6:7], v0, v0, v158
	v_div_scale_f32 v141, s[6:7], v1, v1, v156
	v_rcp_f32_e32 v144, v140
	v_rcp_f32_e32 v145, v141
	v_div_scale_f32 v142, vcc, v158, v0, v158
	v_div_scale_f32 v143, s[6:7], v156, v1, v156
	v_fma_f32 v146, -v140, v144, 1.0
	v_fma_f32 v147, -v141, v145, 1.0
	v_fmac_f32_e32 v144, v146, v144
	v_fmac_f32_e32 v145, v147, v145
	v_mul_f32_e32 v148, v142, v144
	v_mul_f32_e32 v149, v143, v145
	v_fma_f32 v146, -v140, v148, v142
	v_fma_f32 v147, -v141, v149, v143
	v_fmac_f32_e32 v148, v146, v144
	v_fmac_f32_e32 v149, v147, v145
	v_fma_f32 v146, -v140, v148, v142
	v_fma_f32 v147, -v141, v149, v143
	v_div_fmas_f32 v146, v146, v144, v148
	s_mov_b64 vcc, s[6:7]
	v_div_fixup_f32 v0, v146, v0, v158
	s_nop 1
	v_div_fmas_f32 v147, v147, v145, v149
	v_div_fixup_f32 v1, v147, v1, v156
	v_div_scale_f32 v140, s[6:7], v2, v2, v167
	v_div_scale_f32 v141, s[6:7], v3, v3, v157
	v_rcp_f32_e32 v144, v140
	v_rcp_f32_e32 v145, v141
	v_div_scale_f32 v142, vcc, v167, v2, v167
	v_div_scale_f32 v143, s[6:7], v157, v3, v157
	v_fma_f32 v146, -v140, v144, 1.0
	v_fma_f32 v147, -v141, v145, 1.0
	v_fmac_f32_e32 v144, v146, v144
	v_fmac_f32_e32 v145, v147, v145
	v_mul_f32_e32 v148, v142, v144
	v_mul_f32_e32 v149, v143, v145
	v_fma_f32 v146, -v140, v148, v142
	v_fma_f32 v147, -v141, v149, v143
	v_fmac_f32_e32 v148, v146, v144
	v_fmac_f32_e32 v149, v147, v145
	v_fma_f32 v146, -v140, v148, v142
	v_fma_f32 v147, -v141, v149, v143
	v_div_fmas_f32 v146, v146, v144, v148
	s_mov_b64 vcc, s[6:7]
	v_div_fixup_f32 v2, v146, v2, v167
	s_nop 1
	v_div_fmas_f32 v147, v147, v145, v149
	v_div_fixup_f32 v3, v147, v3, v157
	v_cvt_pk_bf16_f32 v0, v0, v1
	v_cvt_pk_bf16_f32 v1, v2, v3
	v_cndmask_b32_e64 v6, v4, v0, s[8:9]
	v_cndmask_b32_e64 v7, v5, v1, s[8:9]
	v_cndmask_b32_e64 v2, v0, v4, s[8:9]
	v_cndmask_b32_e64 v3, v1, v5, s[8:9]
	ds_permute_b32 v4, v159, v6
	ds_permute_b32 v5, v159, v7
	ds_permute_b32 v0, v166, v2
	ds_permute_b32 v1, v166, v3
	s_waitcnt lgkmcnt(4)
	v_cndmask_b32_e64 v38, v32, v36, s[10:11]
	v_cndmask_b32_e64 v39, v33, v37, s[10:11]
	v_cndmask_b32_e64 v36, v36, v32, s[10:11]
	v_cndmask_b32_e64 v37, v37, v33, s[10:11]
	v_add_u32_e32 v169, 0x58000, v168
	global_store_dwordx4 v169, v[36:39], s[12:13]
	s_waitcnt lgkmcnt(0)
	v_cndmask_b32_e64 v6, v0, v4, s[10:11]
	v_cndmask_b32_e64 v7, v1, v5, s[10:11]
	v_cndmask_b32_e64 v4, v4, v0, s[10:11]
	v_cndmask_b32_e64 v5, v5, v1, s[10:11]
	v_add_u32_e32 v169, 0x58100, v168
	global_store_dwordx4 v169, v[4:7], s[12:13]
	s_mov_b64 s[8:9], s[26:27]
	s_mov_b64 s[10:11], s[24:25]
	s_mov_b32 s7, s20
	s_mov_b32 s6, s22
	s_and_b64 vcc, exec, s[4:5]
	s_cbranch_vccz .LBB0_1174
	s_waitcnt vmcnt(0)
	s_cmpk_gt_u32 s30, 0xff
	s_cbranch_scc1 .LBB0_1181
	s_barrier
